# pool token loop: chunk-invariant 1/w computed once (same IEEE div sequence), per-token division only near sequence start
# baseline (speedup 1.0000x reference)
; __device__ __forceinline__ unsigned pk2(float lo, float hi) { f32x2 v = {lo, hi}; bf16x2_t b = __builtin_convertvector(v, bf16x2_t); return __builtin_bit_cast(unsigned, b); }
; __device__ __forceinline__ void pool_phase(const float* __restrict__ x, const bf16_t* __restrict__ x16, const float* __restrict__ g, const float* rsq, bf16_t* __restrict__ pooled, LAS unsigned char* lds, int tid, int wid, int lane, int bid) {
;     ...
;         __syncthreads();
;         const int c = tid * 4, w = 2 << (c >> 9);
;         const f32x4 gv = *(const f32x4*)(g + c);
;         f32x4 S = {0.f, 0.f, 0.f, 0.f};
;         for (int j = 1; j < w; ++j) { const int r = t0 - j; if (r >= bstart) S += ldx4(x, x16, (size_t)r * DM + c) * rs[15 - j]; }
;         for (int tt = 0; tt < 32; ++tt) { const int r = t0 + tt;
;             const f32x4 h = ldx4(x, x16, (size_t)r * DM + c) * rs[15 + tt];
;             S += h;
;             const int tin = r - bstart; const float inv = 1.0f / (float)(tin + 1 < w ? tin + 1 : w);
;             const f32x4 p = (S * inv - h) * gv;
;             u32x2 o; o.x = pk2(p[0], p[1]); o.y = pk2(p[2], p[3]); *(u32x2*)(pooled + (size_t)r * DM + c) = o;
;             const int ro = r - w + 1; if (ro >= bstart) S -= ldx4(x, x16, (size_t)ro * DM + c) * rs[ro - (t0 - 15)]; }
.LBB0_77:
	v_mov_b32_e32 v6, v4
	v_mov_b32_e32 v7, v4
	v_mov_b32_e32 v5, v4
	v_mov_b64_e32 v[8:9], v[6:7]
	v_mov_b64_e32 v[6:7], v[4:5]
	s_waitcnt lgkmcnt(0)
	s_barrier
	v_readfirstlane_b32 s15, v22
	v_lshlrev_b32_e32 v66, 2, v29
	v_min_u32_e32 v66, 0xb8, v66
	ds_read_b32 v37, v66
	s_mov_b32 s13, 0
	s_mov_b32 s17, s14
	s_sub_i32 s31, s14, s44
	s_sub_i32 s28, s14, s15
	s_add_i32 s28, s28, 1
	s_sub_i32 s30, 16, s15
	s_mov_b32 s29, 15
	v_mov_b32_e32 v40, 0
	v_mov_b32_e32 v41, 0
	v_mov_b32_e32 v42, 0
	v_mov_b32_e32 v43, 0
	v_cvt_f32_i32_e32 v39, s15
	v_div_scale_f32 v44, vcc, v39, v39, 1.0
	v_rcp_f32_e32 v45, v44
	v_div_scale_f32 v46, vcc, 1.0, v39, 1.0
	v_fma_f32 v47, -v44, v45, 1.0
	v_fmac_f32_e32 v45, v47, v45
	v_mul_f32_e32 v47, v46, v45
	v_fma_f32 v48, -v44, v47, v46
	v_fmac_f32_e32 v47, v48, v45
	v_fma_f32 v44, -v44, v47, v46
	v_div_fmas_f32 v44, v44, v45, v47
	v_div_fixup_f32 v67, v44, v39, 1.0
	s_sub_i32 s34, s14, 1
	s_max_i32 s34, s34, s44
	s_lshl_b32 s12, s34, 13
	v_lshl_add_u64 v[60:61], v[12:13], 0, s[12:13]
	global_load_dwordx4 v[148:151], v[60:61], off
	s_sub_i32 s34, s14, 2
	s_max_i32 s34, s34, s44
	s_lshl_b32 s12, s34, 13
	v_lshl_add_u64 v[60:61], v[12:13], 0, s[12:13]
	global_load_dwordx4 v[152:155], v[60:61], off
	s_sub_i32 s34, s14, 3
	s_max_i32 s34, s34, s44
	s_lshl_b32 s12, s34, 13
	v_lshl_add_u64 v[60:61], v[12:13], 0, s[12:13]
	global_load_dwordx4 v[156:159], v[60:61], off
	s_sub_i32 s34, s14, 4
	s_max_i32 s34, s34, s44
	s_lshl_b32 s12, s34, 13
	v_lshl_add_u64 v[60:61], v[12:13], 0, s[12:13]
	global_load_dwordx4 v[160:163], v[60:61], off
	s_sub_i32 s34, s14, 5
	s_max_i32 s34, s34, s44
	s_lshl_b32 s12, s34, 13
	v_lshl_add_u64 v[60:61], v[12:13], 0, s[12:13]
	global_load_dwordx4 v[164:167], v[60:61], off
	s_sub_i32 s34, s14, 6
	s_max_i32 s34, s34, s44
	s_lshl_b32 s12, s34, 13
	v_lshl_add_u64 v[60:61], v[12:13], 0, s[12:13]
	global_load_dwordx4 v[168:171], v[60:61], off
	s_sub_i32 s34, s14, 7
	s_max_i32 s34, s34, s44
	s_lshl_b32 s12, s34, 13
	v_lshl_add_u64 v[60:61], v[12:13], 0, s[12:13]
	global_load_dwordx4 v[172:175], v[60:61], off
	s_sub_i32 s34, s14, 8
	s_max_i32 s34, s34, s44
	s_lshl_b32 s12, s34, 13
	v_lshl_add_u64 v[60:61], v[12:13], 0, s[12:13]
	global_load_dwordx4 v[176:179], v[60:61], off
	s_sub_i32 s34, s14, 9
	s_max_i32 s34, s34, s44
	s_lshl_b32 s12, s34, 13
	v_lshl_add_u64 v[60:61], v[12:13], 0, s[12:13]
	global_load_dwordx4 v[180:183], v[60:61], off
	s_sub_i32 s34, s14, 10
	s_max_i32 s34, s34, s44
	s_lshl_b32 s12, s34, 13
	v_lshl_add_u64 v[60:61], v[12:13], 0, s[12:13]
	global_load_dwordx4 v[184:187], v[60:61], off
	s_sub_i32 s34, s14, 11
	s_max_i32 s34, s34, s44
	s_lshl_b32 s12, s34, 13
	v_lshl_add_u64 v[60:61], v[12:13], 0, s[12:13]
	global_load_dwordx4 v[188:191], v[60:61], off
	s_sub_i32 s34, s14, 12
	s_max_i32 s34, s34, s44
	s_lshl_b32 s12, s34, 13
	v_lshl_add_u64 v[60:61], v[12:13], 0, s[12:13]
	global_load_dwordx4 v[192:195], v[60:61], off
	s_sub_i32 s34, s14, 13
	s_max_i32 s34, s34, s44
	s_lshl_b32 s12, s34, 13
	v_lshl_add_u64 v[60:61], v[12:13], 0, s[12:13]
	global_load_dwordx4 v[196:199], v[60:61], off
	s_sub_i32 s34, s14, 14
	s_max_i32 s34, s34, s44
	s_lshl_b32 s12, s34, 13
	v_lshl_add_u64 v[60:61], v[12:13], 0, s[12:13]
	global_load_dwordx4 v[200:203], v[60:61], off
	s_sub_i32 s34, s14, 15
	s_max_i32 s34, s34, s44
	s_lshl_b32 s12, s34, 13
	v_lshl_add_u64 v[60:61], v[12:13], 0, s[12:13]
	global_load_dwordx4 v[208:211], v[60:61], off
	s_add_i32 s34, s17, 0
	s_lshl_b32 s12, s34, 13
	v_lshl_add_u64 v[60:61], v[12:13], 0, s[12:13]
	global_load_dwordx4 v[84:87], v[60:61], off
	s_add_i32 s34, s28, 0
	s_max_i32 s34, s34, s44
	s_lshl_b32 s12, s34, 13
	v_lshl_add_u64 v[60:61], v[12:13], 0, s[12:13]
	global_load_dwordx4 v[88:91], v[60:61], off
	s_add_i32 s34, s17, 1
	s_lshl_b32 s12, s34, 13
	v_lshl_add_u64 v[60:61], v[12:13], 0, s[12:13]
	global_load_dwordx4 v[92:95], v[60:61], off
	s_add_i32 s34, s28, 1
	s_max_i32 s34, s34, s44
	s_lshl_b32 s12, s34, 13
	v_lshl_add_u64 v[60:61], v[12:13], 0, s[12:13]
	global_load_dwordx4 v[96:99], v[60:61], off
	s_add_i32 s34, s17, 2
	s_lshl_b32 s12, s34, 13
	v_lshl_add_u64 v[60:61], v[12:13], 0, s[12:13]
	global_load_dwordx4 v[100:103], v[60:61], off
	s_add_i32 s34, s28, 2
	s_max_i32 s34, s34, s44
	s_lshl_b32 s12, s34, 13
	v_lshl_add_u64 v[60:61], v[12:13], 0, s[12:13]
	global_load_dwordx4 v[104:107], v[60:61], off
	s_add_i32 s34, s17, 3
	s_lshl_b32 s12, s34, 13
	v_lshl_add_u64 v[60:61], v[12:13], 0, s[12:13]
	global_load_dwordx4 v[108:111], v[60:61], off
	s_add_i32 s34, s28, 3
	s_max_i32 s34, s34, s44
	s_lshl_b32 s12, s34, 13
	v_lshl_add_u64 v[60:61], v[12:13], 0, s[12:13]
	global_load_dwordx4 v[112:115], v[60:61], off
	s_add_i32 s34, s17, 4
	s_lshl_b32 s12, s34, 13
	v_lshl_add_u64 v[60:61], v[12:13], 0, s[12:13]
	global_load_dwordx4 v[116:119], v[60:61], off
	s_add_i32 s34, s28, 4
	s_max_i32 s34, s34, s44
	s_lshl_b32 s12, s34, 13
	v_lshl_add_u64 v[60:61], v[12:13], 0, s[12:13]
	global_load_dwordx4 v[120:123], v[60:61], off
	s_add_i32 s34, s17, 5
	s_lshl_b32 s12, s34, 13
	v_lshl_add_u64 v[60:61], v[12:13], 0, s[12:13]
	global_load_dwordx4 v[124:127], v[60:61], off
	s_add_i32 s34, s28, 5
	s_max_i32 s34, s34, s44
	s_lshl_b32 s12, s34, 13
	v_lshl_add_u64 v[60:61], v[12:13], 0, s[12:13]
	global_load_dwordx4 v[128:131], v[60:61], off
	s_add_i32 s34, s17, 6
	s_lshl_b32 s12, s34, 13
	v_lshl_add_u64 v[60:61], v[12:13], 0, s[12:13]
	global_load_dwordx4 v[132:135], v[60:61], off
	s_add_i32 s34, s28, 6
	s_max_i32 s34, s34, s44
	s_lshl_b32 s12, s34, 13
	v_lshl_add_u64 v[60:61], v[12:13], 0, s[12:13]
	global_load_dwordx4 v[136:139], v[60:61], off
	s_add_i32 s34, s17, 7
	s_lshl_b32 s12, s34, 13
	v_lshl_add_u64 v[60:61], v[12:13], 0, s[12:13]
	global_load_dwordx4 v[140:143], v[60:61], off
	s_add_i32 s34, s28, 7
	s_max_i32 s34, s34, s44
	s_lshl_b32 s12, s34, 13
	v_lshl_add_u64 v[60:61], v[12:13], 0, s[12:13]
	global_load_dwordx4 v[144:147], v[60:61], off
	s_waitcnt lgkmcnt(0)
	s_cmp_le_i32 s15, 1
	s_cbranch_scc1 .LplA_init_done
; __device__ __forceinline__ void pool_phase(const float* __restrict__ x, const bf16_t* __restrict__ x16, const float* __restrict__ g, const float* rsq, bf16_t* __restrict__ pooled, LAS unsigned char* lds, int tid, int wid, int lane, int bid) {
;     ...
;         f32x4 S = {0.f, 0.f, 0.f, 0.f};
;         for (int j = 1; j < w; ++j) { const int r = t0 - j; if (r >= bstart) S += ldx4(x, x16, (size_t)r * DM + c) * rs[15 - j]; }
	s_sub_i32 s34, s14, 1
	s_cmp_lt_i32 s34, s44
	s_cbranch_scc1 .LplA_init_done
	v_readlane_b32 s35, v37, 14
	s_waitcnt vmcnt(30)
	s_nop 1
	v_fma_f32 v40, v148, s35, v40
	v_fma_f32 v41, v149, s35, v41
	v_fma_f32 v42, v150, s35, v42
	v_fma_f32 v43, v151, s35, v43
	s_cmp_le_i32 s15, 2
	s_cbranch_scc1 .LplA_init_done
	s_sub_i32 s34, s14, 2
	s_cmp_lt_i32 s34, s44
	s_cbranch_scc1 .LplA_init_done
	v_readlane_b32 s35, v37, 13
	s_waitcnt vmcnt(29)
	s_nop 1
	v_fma_f32 v40, v152, s35, v40
	v_fma_f32 v41, v153, s35, v41
	v_fma_f32 v42, v154, s35, v42
	v_fma_f32 v43, v155, s35, v43
	s_cmp_le_i32 s15, 3
	s_cbranch_scc1 .LplA_init_done
	s_sub_i32 s34, s14, 3
	s_cmp_lt_i32 s34, s44
	s_cbranch_scc1 .LplA_init_done
	v_readlane_b32 s35, v37, 12
	s_waitcnt vmcnt(28)
	s_nop 1
	v_fma_f32 v40, v156, s35, v40
	v_fma_f32 v41, v157, s35, v41
	v_fma_f32 v42, v158, s35, v42
	v_fma_f32 v43, v159, s35, v43
	s_cmp_le_i32 s15, 4
	s_cbranch_scc1 .LplA_init_done
	s_sub_i32 s34, s14, 4
	s_cmp_lt_i32 s34, s44
	s_cbranch_scc1 .LplA_init_done
	v_readlane_b32 s35, v37, 11
	s_waitcnt vmcnt(27)
	s_nop 1
	v_fma_f32 v40, v160, s35, v40
	v_fma_f32 v41, v161, s35, v41
	v_fma_f32 v42, v162, s35, v42
	v_fma_f32 v43, v163, s35, v43
	s_cmp_le_i32 s15, 5
	s_cbranch_scc1 .LplA_init_done
	s_sub_i32 s34, s14, 5
	s_cmp_lt_i32 s34, s44
	s_cbranch_scc1 .LplA_init_done
	v_readlane_b32 s35, v37, 10
	s_waitcnt vmcnt(26)
	s_nop 1
	v_fma_f32 v40, v164, s35, v40
	v_fma_f32 v41, v165, s35, v41
	v_fma_f32 v42, v166, s35, v42
	v_fma_f32 v43, v167, s35, v43
	s_cmp_le_i32 s15, 6
	s_cbranch_scc1 .LplA_init_done
	s_sub_i32 s34, s14, 6
	s_cmp_lt_i32 s34, s44
	s_cbranch_scc1 .LplA_init_done
	v_readlane_b32 s35, v37, 9
	s_waitcnt vmcnt(25)
	s_nop 1
	v_fma_f32 v40, v168, s35, v40
	v_fma_f32 v41, v169, s35, v41
	v_fma_f32 v42, v170, s35, v42
	v_fma_f32 v43, v171, s35, v43
	s_cmp_le_i32 s15, 7
	s_cbranch_scc1 .LplA_init_done
	s_sub_i32 s34, s14, 7
	s_cmp_lt_i32 s34, s44
	s_cbranch_scc1 .LplA_init_done
	v_readlane_b32 s35, v37, 8
	s_waitcnt vmcnt(24)
	s_nop 1
	v_fma_f32 v40, v172, s35, v40
	v_fma_f32 v41, v173, s35, v41
	v_fma_f32 v42, v174, s35, v42
	v_fma_f32 v43, v175, s35, v43
	s_cmp_le_i32 s15, 8
	s_cbranch_scc1 .LplA_init_done
	s_sub_i32 s34, s14, 8
	s_cmp_lt_i32 s34, s44
	s_cbranch_scc1 .LplA_init_done
	v_readlane_b32 s35, v37, 7
	s_waitcnt vmcnt(23)
	s_nop 1
	v_fma_f32 v40, v176, s35, v40
	v_fma_f32 v41, v177, s35, v41
	v_fma_f32 v42, v178, s35, v42
	v_fma_f32 v43, v179, s35, v43
	s_cmp_le_i32 s15, 9
	s_cbranch_scc1 .LplA_init_done
	s_sub_i32 s34, s14, 9
	s_cmp_lt_i32 s34, s44
	s_cbranch_scc1 .LplA_init_done
	v_readlane_b32 s35, v37, 6
	s_waitcnt vmcnt(22)
	s_nop 1
	v_fma_f32 v40, v180, s35, v40
	v_fma_f32 v41, v181, s35, v41
	v_fma_f32 v42, v182, s35, v42
	v_fma_f32 v43, v183, s35, v43
	s_cmp_le_i32 s15, 10
	s_cbranch_scc1 .LplA_init_done
	s_sub_i32 s34, s14, 10
	s_cmp_lt_i32 s34, s44
	s_cbranch_scc1 .LplA_init_done
	v_readlane_b32 s35, v37, 5
	s_waitcnt vmcnt(21)
	s_nop 1
	v_fma_f32 v40, v184, s35, v40
	v_fma_f32 v41, v185, s35, v41
	v_fma_f32 v42, v186, s35, v42
	v_fma_f32 v43, v187, s35, v43
	s_cmp_le_i32 s15, 11
	s_cbranch_scc1 .LplA_init_done
	s_sub_i32 s34, s14, 11
	s_cmp_lt_i32 s34, s44
	s_cbranch_scc1 .LplA_init_done
	v_readlane_b32 s35, v37, 4
	s_waitcnt vmcnt(20)
	s_nop 1
	v_fma_f32 v40, v188, s35, v40
	v_fma_f32 v41, v189, s35, v41
	v_fma_f32 v42, v190, s35, v42
	v_fma_f32 v43, v191, s35, v43
	s_cmp_le_i32 s15, 12
	s_cbranch_scc1 .LplA_init_done
	s_sub_i32 s34, s14, 12
	s_cmp_lt_i32 s34, s44
	s_cbranch_scc1 .LplA_init_done
	v_readlane_b32 s35, v37, 3
	s_waitcnt vmcnt(19)
	s_nop 1
	v_fma_f32 v40, v192, s35, v40
	v_fma_f32 v41, v193, s35, v41
	v_fma_f32 v42, v194, s35, v42
	v_fma_f32 v43, v195, s35, v43
	s_cmp_le_i32 s15, 13
	s_cbranch_scc1 .LplA_init_done
	s_sub_i32 s34, s14, 13
	s_cmp_lt_i32 s34, s44
	s_cbranch_scc1 .LplA_init_done
	v_readlane_b32 s35, v37, 2
	s_waitcnt vmcnt(18)
	s_nop 1
	v_fma_f32 v40, v196, s35, v40
	v_fma_f32 v41, v197, s35, v41
	v_fma_f32 v42, v198, s35, v42
	v_fma_f32 v43, v199, s35, v43
	s_cmp_le_i32 s15, 14
	s_cbranch_scc1 .LplA_init_done
	s_sub_i32 s34, s14, 14
	s_cmp_lt_i32 s34, s44
	s_cbranch_scc1 .LplA_init_done
	v_readlane_b32 s35, v37, 1
	s_waitcnt vmcnt(17)
	s_nop 1
	v_fma_f32 v40, v200, s35, v40
	v_fma_f32 v41, v201, s35, v41
	v_fma_f32 v42, v202, s35, v42
	v_fma_f32 v43, v203, s35, v43
	s_cmp_le_i32 s15, 15
	s_cbranch_scc1 .LplA_init_done
	s_sub_i32 s34, s14, 15
	s_cmp_lt_i32 s34, s44
	s_cbranch_scc1 .LplA_init_done
	v_readlane_b32 s35, v37, 0
	s_waitcnt vmcnt(16)
	s_nop 1
	v_fma_f32 v40, v208, s35, v40
	v_fma_f32 v41, v209, s35, v41
	v_fma_f32 v42, v210, s35, v42
	v_fma_f32 v43, v211, s35, v43
; __device__ __forceinline__ unsigned pk2(float lo, float hi) { f32x2 v = {lo, hi}; bf16x2_t b = __builtin_convertvector(v, bf16x2_t); return __builtin_bit_cast(unsigned, b); }
; __device__ __forceinline__ void pool_phase(const float* __restrict__ x, const bf16_t* __restrict__ x16, const float* __restrict__ g, const float* rsq, bf16_t* __restrict__ pooled, LAS unsigned char* lds, int tid, int wid, int lane, int bid) {
;     ...
;         for (int tt = 0; tt < 32; ++tt) { const int r = t0 + tt;
;             const f32x4 h = ldx4(x, x16, (size_t)r * DM + c) * rs[15 + tt];
;             S += h;
;             const int tin = r - bstart; const float inv = 1.0f / (float)(tin + 1 < w ? tin + 1 : w);
;             const f32x4 p = (S * inv - h) * gv;
;             u32x2 o; o.x = pk2(p[0], p[1]); o.y = pk2(p[2], p[3]); *(u32x2*)(pooled + (size_t)r * DM + c) = o;
;             const int ro = r - w + 1; if (ro >= bstart) S -= ldx4(x, x16, (size_t)ro * DM + c) * rs[ro - (t0 - 15)]; }
.LplA_init_done:
.LplA_loop:
	s_add_i32 s37, s29, 0
	v_readlane_b32 s35, v37, s37
	s_add_i32 s34, s31, 1
	s_cmp_ge_i32 s34, s15
	s_cbranch_scc1 .LplA_invw0
	v_cvt_f32_i32_e32 v39, s34
	v_div_scale_f32 v44, vcc, v39, v39, 1.0
	v_rcp_f32_e32 v45, v44
	v_div_scale_f32 v46, vcc, 1.0, v39, 1.0
	v_fma_f32 v47, -v44, v45, 1.0
	v_fmac_f32_e32 v45, v47, v45
	v_mul_f32_e32 v47, v46, v45
	v_fma_f32 v48, -v44, v47, v46
	v_fmac_f32_e32 v47, v48, v45
	v_fma_f32 v44, -v44, v47, v46
	v_div_fmas_f32 v44, v44, v45, v47
	v_div_fixup_f32 v38, v44, v39, 1.0
	s_branch .LplA_invd0
.LplA_invw0:
	v_mov_b32_e32 v38, v67
.LplA_invd0:
	s_waitcnt vmcnt(15)
	v_mul_f32_e32 v52, s35, v84
	v_mul_f32_e32 v53, s35, v85
	v_mul_f32_e32 v54, s35, v86
	v_mul_f32_e32 v55, s35, v87
	v_fma_f32 v40, v84, s35, v40
	v_fma_f32 v41, v85, s35, v41
	v_fma_f32 v42, v86, s35, v42
	v_fma_f32 v43, v87, s35, v43
	v_fma_f32 v56, v38, v40, -v52
	v_fma_f32 v57, v38, v41, -v53
	v_fma_f32 v58, v38, v42, -v54
	v_fma_f32 v59, v38, v43, -v55
	v_mul_f32_e32 v56, v0, v56
	v_mul_f32_e32 v57, v1, v57
	v_mul_f32_e32 v58, v2, v58
	v_mul_f32_e32 v59, v3, v59
	v_cvt_pk_bf16_f32 v64, v56, v57
	v_cvt_pk_bf16_f32 v65, v58, v59
	s_add_i32 s34, s17, 0
	s_lshl_b32 s12, s34, 12
	v_lshl_add_u64 v[62:63], v[10:11], 0, s[12:13]
	global_store_dwordx2 v[62:63], v[64:65], off
	s_add_i32 s34, s28, 0
	s_cmp_lt_i32 s34, s44
	s_cbranch_scc1 .LplA_skip0
	s_add_i32 s37, s30, 0
	v_readlane_b32 s36, v37, s37
	s_waitcnt vmcnt(15)
	s_nop 1
	v_fma_f32 v40, -v88, s36, v40
	v_fma_f32 v41, -v89, s36, v41
	v_fma_f32 v42, -v90, s36, v42
	v_fma_f32 v43, -v91, s36, v43
.LplA_skip0:
	s_add_i32 s34, s17, 8
	s_min_i32 s34, s34, 0x1fff
	s_lshl_b32 s12, s34, 13
	v_lshl_add_u64 v[60:61], v[12:13], 0, s[12:13]
	global_load_dwordx4 v[84:87], v[60:61], off
	s_add_i32 s34, s28, 8
	s_max_i32 s34, s34, s44
	s_min_i32 s34, s34, 0x1fff
	s_lshl_b32 s12, s34, 13
	v_lshl_add_u64 v[60:61], v[12:13], 0, s[12:13]
	global_load_dwordx4 v[88:91], v[60:61], off
	s_add_i32 s37, s29, 1
	v_readlane_b32 s35, v37, s37
	s_add_i32 s34, s31, 2
	s_cmp_ge_i32 s34, s15
	s_cbranch_scc1 .LplA_invw1
	v_cvt_f32_i32_e32 v39, s34
	v_div_scale_f32 v44, vcc, v39, v39, 1.0
	v_rcp_f32_e32 v45, v44
	v_div_scale_f32 v46, vcc, 1.0, v39, 1.0
	v_fma_f32 v47, -v44, v45, 1.0
	v_fmac_f32_e32 v45, v47, v45
	v_mul_f32_e32 v47, v46, v45
	v_fma_f32 v48, -v44, v47, v46
	v_fmac_f32_e32 v47, v48, v45
	v_fma_f32 v44, -v44, v47, v46
	v_div_fmas_f32 v44, v44, v45, v47
	v_div_fixup_f32 v38, v44, v39, 1.0
	s_branch .LplA_invd1

; __device__ __forceinline__ unsigned pk2(float lo, float hi) { f32x2 v = {lo, hi}; bf16x2_t b = __builtin_convertvector(v, bf16x2_t); return __builtin_bit_cast(unsigned, b); }
; __device__ __forceinline__ void pool_phase(const float* __restrict__ x, const bf16_t* __restrict__ x16, const float* __restrict__ g, const float* rsq, bf16_t* __restrict__ pooled, LAS unsigned char* lds, int tid, int wid, int lane, int bid) {
;     ...
;         for (int tt = 0; tt < 32; ++tt) { const int r = t0 + tt;
;             const f32x4 h = ldx4(x, x16, (size_t)r * DM + c) * rs[15 + tt];
;             S += h;
;             const int tin = r - bstart; const float inv = 1.0f / (float)(tin + 1 < w ? tin + 1 : w);
;             const f32x4 p = (S * inv - h) * gv;
;             u32x2 o; o.x = pk2(p[0], p[1]); o.y = pk2(p[2], p[3]); *(u32x2*)(pooled + (size_t)r * DM + c) = o;
;             const int ro = r - w + 1; if (ro >= bstart) S -= ldx4(x, x16, (size_t)ro * DM + c) * rs[ro - (t0 - 15)]; }
.LplA_invd1:
	s_waitcnt vmcnt(16)
	v_mul_f32_e32 v52, s35, v92
	v_mul_f32_e32 v53, s35, v93
	v_mul_f32_e32 v54, s35, v94
	v_mul_f32_e32 v55, s35, v95
	v_fma_f32 v40, v92, s35, v40
	v_fma_f32 v41, v93, s35, v41
	v_fma_f32 v42, v94, s35, v42
	v_fma_f32 v43, v95, s35, v43
	v_fma_f32 v56, v38, v40, -v52
	v_fma_f32 v57, v38, v41, -v53
	v_fma_f32 v58, v38, v42, -v54
	v_fma_f32 v59, v38, v43, -v55
	v_mul_f32_e32 v56, v0, v56
	v_mul_f32_e32 v57, v1, v57
	v_mul_f32_e32 v58, v2, v58
	v_mul_f32_e32 v59, v3, v59
	v_cvt_pk_bf16_f32 v64, v56, v57
	v_cvt_pk_bf16_f32 v65, v58, v59
	s_add_i32 s34, s17, 1
	s_lshl_b32 s12, s34, 12
	v_lshl_add_u64 v[62:63], v[10:11], 0, s[12:13]
	global_store_dwordx2 v[62:63], v[64:65], off
	s_add_i32 s34, s28, 1
	s_cmp_lt_i32 s34, s44
	s_cbranch_scc1 .LplA_skip1
	s_add_i32 s37, s30, 1
	v_readlane_b32 s36, v37, s37
	s_waitcnt vmcnt(16)
	s_nop 1
	v_fma_f32 v40, -v96, s36, v40
	v_fma_f32 v41, -v97, s36, v41
	v_fma_f32 v42, -v98, s36, v42
	v_fma_f32 v43, -v99, s36, v43
.LplA_skip1:
	s_add_i32 s34, s17, 9
	s_min_i32 s34, s34, 0x1fff
	s_lshl_b32 s12, s34, 13
	v_lshl_add_u64 v[60:61], v[12:13], 0, s[12:13]
	global_load_dwordx4 v[92:95], v[60:61], off
	s_add_i32 s34, s28, 9
	s_max_i32 s34, s34, s44
	s_min_i32 s34, s34, 0x1fff
	s_lshl_b32 s12, s34, 13
	v_lshl_add_u64 v[60:61], v[12:13], 0, s[12:13]
	global_load_dwordx4 v[96:99], v[60:61], off
	s_add_i32 s37, s29, 2
	v_readlane_b32 s35, v37, s37
	s_add_i32 s34, s31, 3
	s_cmp_ge_i32 s34, s15
	s_cbranch_scc1 .LplA_invw2
	v_cvt_f32_i32_e32 v39, s34
	v_div_scale_f32 v44, vcc, v39, v39, 1.0
	v_rcp_f32_e32 v45, v44
	v_div_scale_f32 v46, vcc, 1.0, v39, 1.0
	v_fma_f32 v47, -v44, v45, 1.0
	v_fmac_f32_e32 v45, v47, v45
	v_mul_f32_e32 v47, v46, v45
	v_fma_f32 v48, -v44, v47, v46
	v_fmac_f32_e32 v47, v48, v45
	v_fma_f32 v44, -v44, v47, v46
	v_div_fmas_f32 v44, v44, v45, v47
	v_div_fixup_f32 v38, v44, v39, 1.0
	s_branch .LplA_invd2

; __device__ __forceinline__ unsigned pk2(float lo, float hi) { f32x2 v = {lo, hi}; bf16x2_t b = __builtin_convertvector(v, bf16x2_t); return __builtin_bit_cast(unsigned, b); }
; __device__ __forceinline__ void pool_phase(const float* __restrict__ x, const bf16_t* __restrict__ x16, const float* __restrict__ g, const float* rsq, bf16_t* __restrict__ pooled, LAS unsigned char* lds, int tid, int wid, int lane, int bid) {
;     ...
;         for (int tt = 0; tt < 32; ++tt) { const int r = t0 + tt;
;             const f32x4 h = ldx4(x, x16, (size_t)r * DM + c) * rs[15 + tt];
;             S += h;
;             const int tin = r - bstart; const float inv = 1.0f / (float)(tin + 1 < w ? tin + 1 : w);
;             const f32x4 p = (S * inv - h) * gv;
;             u32x2 o; o.x = pk2(p[0], p[1]); o.y = pk2(p[2], p[3]); *(u32x2*)(pooled + (size_t)r * DM + c) = o;
;             const int ro = r - w + 1; if (ro >= bstart) S -= ldx4(x, x16, (size_t)ro * DM + c) * rs[ro - (t0 - 15)]; }
.LplA_invd2:
	s_waitcnt vmcnt(17)
	v_mul_f32_e32 v52, s35, v100
	v_mul_f32_e32 v53, s35, v101
	v_mul_f32_e32 v54, s35, v102
	v_mul_f32_e32 v55, s35, v103
	v_fma_f32 v40, v100, s35, v40
	v_fma_f32 v41, v101, s35, v41
	v_fma_f32 v42, v102, s35, v42
	v_fma_f32 v43, v103, s35, v43
	v_fma_f32 v56, v38, v40, -v52
	v_fma_f32 v57, v38, v41, -v53
	v_fma_f32 v58, v38, v42, -v54
	v_fma_f32 v59, v38, v43, -v55
	v_mul_f32_e32 v56, v0, v56
	v_mul_f32_e32 v57, v1, v57
	v_mul_f32_e32 v58, v2, v58
	v_mul_f32_e32 v59, v3, v59
	v_cvt_pk_bf16_f32 v64, v56, v57
	v_cvt_pk_bf16_f32 v65, v58, v59
	s_add_i32 s34, s17, 2
	s_lshl_b32 s12, s34, 12
	v_lshl_add_u64 v[62:63], v[10:11], 0, s[12:13]
	global_store_dwordx2 v[62:63], v[64:65], off
	s_add_i32 s34, s28, 2
	s_cmp_lt_i32 s34, s44
	s_cbranch_scc1 .LplA_skip2
	s_add_i32 s37, s30, 2
	v_readlane_b32 s36, v37, s37
	s_waitcnt vmcnt(17)
	s_nop 1
	v_fma_f32 v40, -v104, s36, v40
	v_fma_f32 v41, -v105, s36, v41
	v_fma_f32 v42, -v106, s36, v42
	v_fma_f32 v43, -v107, s36, v43
.LplA_skip2:
	s_add_i32 s34, s17, 10
	s_min_i32 s34, s34, 0x1fff
	s_lshl_b32 s12, s34, 13
	v_lshl_add_u64 v[60:61], v[12:13], 0, s[12:13]
	global_load_dwordx4 v[100:103], v[60:61], off
	s_add_i32 s34, s28, 10
	s_max_i32 s34, s34, s44
	s_min_i32 s34, s34, 0x1fff
	s_lshl_b32 s12, s34, 13
	v_lshl_add_u64 v[60:61], v[12:13], 0, s[12:13]
	global_load_dwordx4 v[104:107], v[60:61], off
	s_add_i32 s37, s29, 3
	v_readlane_b32 s35, v37, s37
	s_add_i32 s34, s31, 4
	s_cmp_ge_i32 s34, s15
	s_cbranch_scc1 .LplA_invw3
	v_cvt_f32_i32_e32 v39, s34
	v_div_scale_f32 v44, vcc, v39, v39, 1.0
	v_rcp_f32_e32 v45, v44
	v_div_scale_f32 v46, vcc, 1.0, v39, 1.0
	v_fma_f32 v47, -v44, v45, 1.0
	v_fmac_f32_e32 v45, v47, v45
	v_mul_f32_e32 v47, v46, v45
	v_fma_f32 v48, -v44, v47, v46
	v_fmac_f32_e32 v47, v48, v45
	v_fma_f32 v44, -v44, v47, v46
	v_div_fmas_f32 v44, v44, v45, v47
	v_div_fixup_f32 v38, v44, v39, 1.0
	s_branch .LplA_invd3

; __device__ __forceinline__ unsigned pk2(float lo, float hi) { f32x2 v = {lo, hi}; bf16x2_t b = __builtin_convertvector(v, bf16x2_t); return __builtin_bit_cast(unsigned, b); }
; __device__ __forceinline__ void pool_phase(const float* __restrict__ x, const bf16_t* __restrict__ x16, const float* __restrict__ g, const float* rsq, bf16_t* __restrict__ pooled, LAS unsigned char* lds, int tid, int wid, int lane, int bid) {
;     ...
;         for (int tt = 0; tt < 32; ++tt) { const int r = t0 + tt;
;             const f32x4 h = ldx4(x, x16, (size_t)r * DM + c) * rs[15 + tt];
;             S += h;
;             const int tin = r - bstart; const float inv = 1.0f / (float)(tin + 1 < w ? tin + 1 : w);
;             const f32x4 p = (S * inv - h) * gv;
;             u32x2 o; o.x = pk2(p[0], p[1]); o.y = pk2(p[2], p[3]); *(u32x2*)(pooled + (size_t)r * DM + c) = o;
;             const int ro = r - w + 1; if (ro >= bstart) S -= ldx4(x, x16, (size_t)ro * DM + c) * rs[ro - (t0 - 15)]; }
.LplA_invd3:
	s_waitcnt vmcnt(18)
	v_mul_f32_e32 v52, s35, v108
	v_mul_f32_e32 v53, s35, v109
	v_mul_f32_e32 v54, s35, v110
	v_mul_f32_e32 v55, s35, v111
	v_fma_f32 v40, v108, s35, v40
	v_fma_f32 v41, v109, s35, v41
	v_fma_f32 v42, v110, s35, v42
	v_fma_f32 v43, v111, s35, v43
	v_fma_f32 v56, v38, v40, -v52
	v_fma_f32 v57, v38, v41, -v53
	v_fma_f32 v58, v38, v42, -v54
	v_fma_f32 v59, v38, v43, -v55
	v_mul_f32_e32 v56, v0, v56
	v_mul_f32_e32 v57, v1, v57
	v_mul_f32_e32 v58, v2, v58
	v_mul_f32_e32 v59, v3, v59
	v_cvt_pk_bf16_f32 v64, v56, v57
	v_cvt_pk_bf16_f32 v65, v58, v59
	s_add_i32 s34, s17, 3
	s_lshl_b32 s12, s34, 12
	v_lshl_add_u64 v[62:63], v[10:11], 0, s[12:13]
	global_store_dwordx2 v[62:63], v[64:65], off
	s_add_i32 s34, s28, 3
	s_cmp_lt_i32 s34, s44
	s_cbranch_scc1 .LplA_skip3
	s_add_i32 s37, s30, 3
	v_readlane_b32 s36, v37, s37
	s_waitcnt vmcnt(18)
	s_nop 1
	v_fma_f32 v40, -v112, s36, v40
	v_fma_f32 v41, -v113, s36, v41
	v_fma_f32 v42, -v114, s36, v42
	v_fma_f32 v43, -v115, s36, v43
.LplA_skip3:
	s_add_i32 s34, s17, 11
	s_min_i32 s34, s34, 0x1fff
	s_lshl_b32 s12, s34, 13
	v_lshl_add_u64 v[60:61], v[12:13], 0, s[12:13]
	global_load_dwordx4 v[108:111], v[60:61], off
	s_add_i32 s34, s28, 11
	s_max_i32 s34, s34, s44
	s_min_i32 s34, s34, 0x1fff
	s_lshl_b32 s12, s34, 13
	v_lshl_add_u64 v[60:61], v[12:13], 0, s[12:13]
	global_load_dwordx4 v[112:115], v[60:61], off
	s_add_i32 s37, s29, 4
	v_readlane_b32 s35, v37, s37
	s_add_i32 s34, s31, 5
	s_cmp_ge_i32 s34, s15
	s_cbranch_scc1 .LplA_invw4
	v_cvt_f32_i32_e32 v39, s34
	v_div_scale_f32 v44, vcc, v39, v39, 1.0
	v_rcp_f32_e32 v45, v44
	v_div_scale_f32 v46, vcc, 1.0, v39, 1.0
	v_fma_f32 v47, -v44, v45, 1.0
	v_fmac_f32_e32 v45, v47, v45
	v_mul_f32_e32 v47, v46, v45
	v_fma_f32 v48, -v44, v47, v46
	v_fmac_f32_e32 v47, v48, v45
	v_fma_f32 v44, -v44, v47, v46
	v_div_fmas_f32 v44, v44, v45, v47
	v_div_fixup_f32 v38, v44, v39, 1.0
	s_branch .LplA_invd4

; __device__ __forceinline__ unsigned pk2(float lo, float hi) { f32x2 v = {lo, hi}; bf16x2_t b = __builtin_convertvector(v, bf16x2_t); return __builtin_bit_cast(unsigned, b); }
; __device__ __forceinline__ void pool_phase(const float* __restrict__ x, const bf16_t* __restrict__ x16, const float* __restrict__ g, const float* rsq, bf16_t* __restrict__ pooled, LAS unsigned char* lds, int tid, int wid, int lane, int bid) {
;     ...
;         for (int tt = 0; tt < 32; ++tt) { const int r = t0 + tt;
;             const f32x4 h = ldx4(x, x16, (size_t)r * DM + c) * rs[15 + tt];
;             S += h;
;             const int tin = r - bstart; const float inv = 1.0f / (float)(tin + 1 < w ? tin + 1 : w);
;             const f32x4 p = (S * inv - h) * gv;
;             u32x2 o; o.x = pk2(p[0], p[1]); o.y = pk2(p[2], p[3]); *(u32x2*)(pooled + (size_t)r * DM + c) = o;
;             const int ro = r - w + 1; if (ro >= bstart) S -= ldx4(x, x16, (size_t)ro * DM + c) * rs[ro - (t0 - 15)]; }
.LplA_invd4:
	s_waitcnt vmcnt(19)
	v_mul_f32_e32 v52, s35, v116
	v_mul_f32_e32 v53, s35, v117
	v_mul_f32_e32 v54, s35, v118
	v_mul_f32_e32 v55, s35, v119
	v_fma_f32 v40, v116, s35, v40
	v_fma_f32 v41, v117, s35, v41
	v_fma_f32 v42, v118, s35, v42
	v_fma_f32 v43, v119, s35, v43
	v_fma_f32 v56, v38, v40, -v52
	v_fma_f32 v57, v38, v41, -v53
	v_fma_f32 v58, v38, v42, -v54
	v_fma_f32 v59, v38, v43, -v55
	v_mul_f32_e32 v56, v0, v56
	v_mul_f32_e32 v57, v1, v57
	v_mul_f32_e32 v58, v2, v58
	v_mul_f32_e32 v59, v3, v59
	v_cvt_pk_bf16_f32 v64, v56, v57
	v_cvt_pk_bf16_f32 v65, v58, v59
	s_add_i32 s34, s17, 4
	s_lshl_b32 s12, s34, 12
	v_lshl_add_u64 v[62:63], v[10:11], 0, s[12:13]
	global_store_dwordx2 v[62:63], v[64:65], off
	s_add_i32 s34, s28, 4
	s_cmp_lt_i32 s34, s44
	s_cbranch_scc1 .LplA_skip4
	s_add_i32 s37, s30, 4
	v_readlane_b32 s36, v37, s37
	s_waitcnt vmcnt(19)
	s_nop 1
	v_fma_f32 v40, -v120, s36, v40
	v_fma_f32 v41, -v121, s36, v41
	v_fma_f32 v42, -v122, s36, v42
	v_fma_f32 v43, -v123, s36, v43
.LplA_skip4:
	s_add_i32 s34, s17, 12
	s_min_i32 s34, s34, 0x1fff
	s_lshl_b32 s12, s34, 13
	v_lshl_add_u64 v[60:61], v[12:13], 0, s[12:13]
	global_load_dwordx4 v[116:119], v[60:61], off
	s_add_i32 s34, s28, 12
	s_max_i32 s34, s34, s44
	s_min_i32 s34, s34, 0x1fff
	s_lshl_b32 s12, s34, 13
	v_lshl_add_u64 v[60:61], v[12:13], 0, s[12:13]
	global_load_dwordx4 v[120:123], v[60:61], off
	s_add_i32 s37, s29, 5
	v_readlane_b32 s35, v37, s37
	s_add_i32 s34, s31, 6
	s_cmp_ge_i32 s34, s15
	s_cbranch_scc1 .LplA_invw5
	v_cvt_f32_i32_e32 v39, s34
	v_div_scale_f32 v44, vcc, v39, v39, 1.0
	v_rcp_f32_e32 v45, v44
	v_div_scale_f32 v46, vcc, 1.0, v39, 1.0
	v_fma_f32 v47, -v44, v45, 1.0
	v_fmac_f32_e32 v45, v47, v45
	v_mul_f32_e32 v47, v46, v45
	v_fma_f32 v48, -v44, v47, v46
	v_fmac_f32_e32 v47, v48, v45
	v_fma_f32 v44, -v44, v47, v46
	v_div_fmas_f32 v44, v44, v45, v47
	v_div_fixup_f32 v38, v44, v39, 1.0
	s_branch .LplA_invd5

; __device__ __forceinline__ unsigned pk2(float lo, float hi) { f32x2 v = {lo, hi}; bf16x2_t b = __builtin_convertvector(v, bf16x2_t); return __builtin_bit_cast(unsigned, b); }
; __device__ __forceinline__ void pool_phase(const float* __restrict__ x, const bf16_t* __restrict__ x16, const float* __restrict__ g, const float* rsq, bf16_t* __restrict__ pooled, LAS unsigned char* lds, int tid, int wid, int lane, int bid) {
;     ...
;         for (int tt = 0; tt < 32; ++tt) { const int r = t0 + tt;
;             const f32x4 h = ldx4(x, x16, (size_t)r * DM + c) * rs[15 + tt];
;             S += h;
;             const int tin = r - bstart; const float inv = 1.0f / (float)(tin + 1 < w ? tin + 1 : w);
;             const f32x4 p = (S * inv - h) * gv;
;             u32x2 o; o.x = pk2(p[0], p[1]); o.y = pk2(p[2], p[3]); *(u32x2*)(pooled + (size_t)r * DM + c) = o;
;             const int ro = r - w + 1; if (ro >= bstart) S -= ldx4(x, x16, (size_t)ro * DM + c) * rs[ro - (t0 - 15)]; }
.LplA_invd5:
	s_waitcnt vmcnt(20)
	v_mul_f32_e32 v52, s35, v124
	v_mul_f32_e32 v53, s35, v125
	v_mul_f32_e32 v54, s35, v126
	v_mul_f32_e32 v55, s35, v127
	v_fma_f32 v40, v124, s35, v40
	v_fma_f32 v41, v125, s35, v41
	v_fma_f32 v42, v126, s35, v42
	v_fma_f32 v43, v127, s35, v43
	v_fma_f32 v56, v38, v40, -v52
	v_fma_f32 v57, v38, v41, -v53
	v_fma_f32 v58, v38, v42, -v54
	v_fma_f32 v59, v38, v43, -v55
	v_mul_f32_e32 v56, v0, v56
	v_mul_f32_e32 v57, v1, v57
	v_mul_f32_e32 v58, v2, v58
	v_mul_f32_e32 v59, v3, v59
	v_cvt_pk_bf16_f32 v64, v56, v57
	v_cvt_pk_bf16_f32 v65, v58, v59
	s_add_i32 s34, s17, 5
	s_lshl_b32 s12, s34, 12
	v_lshl_add_u64 v[62:63], v[10:11], 0, s[12:13]
	global_store_dwordx2 v[62:63], v[64:65], off
	s_add_i32 s34, s28, 5
	s_cmp_lt_i32 s34, s44
	s_cbranch_scc1 .LplA_skip5
	s_add_i32 s37, s30, 5
	v_readlane_b32 s36, v37, s37
	s_waitcnt vmcnt(20)
	s_nop 1
	v_fma_f32 v40, -v128, s36, v40
	v_fma_f32 v41, -v129, s36, v41
	v_fma_f32 v42, -v130, s36, v42
	v_fma_f32 v43, -v131, s36, v43
.LplA_skip5:
	s_add_i32 s34, s17, 13
	s_min_i32 s34, s34, 0x1fff
	s_lshl_b32 s12, s34, 13
	v_lshl_add_u64 v[60:61], v[12:13], 0, s[12:13]
	global_load_dwordx4 v[124:127], v[60:61], off
	s_add_i32 s34, s28, 13
	s_max_i32 s34, s34, s44
	s_min_i32 s34, s34, 0x1fff
	s_lshl_b32 s12, s34, 13
	v_lshl_add_u64 v[60:61], v[12:13], 0, s[12:13]
	global_load_dwordx4 v[128:131], v[60:61], off
	s_add_i32 s37, s29, 6
	v_readlane_b32 s35, v37, s37
	s_add_i32 s34, s31, 7
	s_cmp_ge_i32 s34, s15
	s_cbranch_scc1 .LplA_invw6
	v_cvt_f32_i32_e32 v39, s34
	v_div_scale_f32 v44, vcc, v39, v39, 1.0
	v_rcp_f32_e32 v45, v44
	v_div_scale_f32 v46, vcc, 1.0, v39, 1.0
	v_fma_f32 v47, -v44, v45, 1.0
	v_fmac_f32_e32 v45, v47, v45
	v_mul_f32_e32 v47, v46, v45
	v_fma_f32 v48, -v44, v47, v46
	v_fmac_f32_e32 v47, v48, v45
	v_fma_f32 v44, -v44, v47, v46
	v_div_fmas_f32 v44, v44, v45, v47
	v_div_fixup_f32 v38, v44, v39, 1.0
	s_branch .LplA_invd6

; __device__ __forceinline__ unsigned pk2(float lo, float hi) { f32x2 v = {lo, hi}; bf16x2_t b = __builtin_convertvector(v, bf16x2_t); return __builtin_bit_cast(unsigned, b); }
; __device__ __forceinline__ void pool_phase(const float* __restrict__ x, const bf16_t* __restrict__ x16, const float* __restrict__ g, const float* rsq, bf16_t* __restrict__ pooled, LAS unsigned char* lds, int tid, int wid, int lane, int bid) {
;     ...
;         for (int tt = 0; tt < 32; ++tt) { const int r = t0 + tt;
;             const f32x4 h = ldx4(x, x16, (size_t)r * DM + c) * rs[15 + tt];
;             S += h;
;             const int tin = r - bstart; const float inv = 1.0f / (float)(tin + 1 < w ? tin + 1 : w);
;             const f32x4 p = (S * inv - h) * gv;
;             u32x2 o; o.x = pk2(p[0], p[1]); o.y = pk2(p[2], p[3]); *(u32x2*)(pooled + (size_t)r * DM + c) = o;
;             const int ro = r - w + 1; if (ro >= bstart) S -= ldx4(x, x16, (size_t)ro * DM + c) * rs[ro - (t0 - 15)]; }
.LplA_invd6:
	s_waitcnt vmcnt(21)
	v_mul_f32_e32 v52, s35, v132
	v_mul_f32_e32 v53, s35, v133
	v_mul_f32_e32 v54, s35, v134
	v_mul_f32_e32 v55, s35, v135
	v_fma_f32 v40, v132, s35, v40
	v_fma_f32 v41, v133, s35, v41
	v_fma_f32 v42, v134, s35, v42
	v_fma_f32 v43, v135, s35, v43
	v_fma_f32 v56, v38, v40, -v52
	v_fma_f32 v57, v38, v41, -v53
	v_fma_f32 v58, v38, v42, -v54
	v_fma_f32 v59, v38, v43, -v55
	v_mul_f32_e32 v56, v0, v56
	v_mul_f32_e32 v57, v1, v57
	v_mul_f32_e32 v58, v2, v58
	v_mul_f32_e32 v59, v3, v59
	v_cvt_pk_bf16_f32 v64, v56, v57
	v_cvt_pk_bf16_f32 v65, v58, v59
	s_add_i32 s34, s17, 6
	s_lshl_b32 s12, s34, 12
	v_lshl_add_u64 v[62:63], v[10:11], 0, s[12:13]
	global_store_dwordx2 v[62:63], v[64:65], off
	s_add_i32 s34, s28, 6
	s_cmp_lt_i32 s34, s44
	s_cbranch_scc1 .LplA_skip6
	s_add_i32 s37, s30, 6
	v_readlane_b32 s36, v37, s37
	s_waitcnt vmcnt(21)
	s_nop 1
	v_fma_f32 v40, -v136, s36, v40
	v_fma_f32 v41, -v137, s36, v41
	v_fma_f32 v42, -v138, s36, v42
	v_fma_f32 v43, -v139, s36, v43
.LplA_skip6:
	s_add_i32 s34, s17, 14
	s_min_i32 s34, s34, 0x1fff
	s_lshl_b32 s12, s34, 13
	v_lshl_add_u64 v[60:61], v[12:13], 0, s[12:13]
	global_load_dwordx4 v[132:135], v[60:61], off
	s_add_i32 s34, s28, 14
	s_max_i32 s34, s34, s44
	s_min_i32 s34, s34, 0x1fff
	s_lshl_b32 s12, s34, 13
	v_lshl_add_u64 v[60:61], v[12:13], 0, s[12:13]
	global_load_dwordx4 v[136:139], v[60:61], off
	s_add_i32 s37, s29, 7
	v_readlane_b32 s35, v37, s37
	s_add_i32 s34, s31, 8
	s_cmp_ge_i32 s34, s15
	s_cbranch_scc1 .LplA_invw7
	v_cvt_f32_i32_e32 v39, s34
	v_div_scale_f32 v44, vcc, v39, v39, 1.0
	v_rcp_f32_e32 v45, v44
	v_div_scale_f32 v46, vcc, 1.0, v39, 1.0
	v_fma_f32 v47, -v44, v45, 1.0
	v_fmac_f32_e32 v45, v47, v45
	v_mul_f32_e32 v47, v46, v45
	v_fma_f32 v48, -v44, v47, v46
	v_fmac_f32_e32 v47, v48, v45
	v_fma_f32 v44, -v44, v47, v46
	v_div_fmas_f32 v44, v44, v45, v47
	v_div_fixup_f32 v38, v44, v39, 1.0
	s_branch .LplA_invd7

; __device__ __forceinline__ unsigned pk2(float lo, float hi) { f32x2 v = {lo, hi}; bf16x2_t b = __builtin_convertvector(v, bf16x2_t); return __builtin_bit_cast(unsigned, b); }
; __device__ __forceinline__ void pool_phase(const float* __restrict__ x, const bf16_t* __restrict__ x16, const float* __restrict__ g, const float* rsq, bf16_t* __restrict__ pooled, LAS unsigned char* lds, int tid, int wid, int lane, int bid) {
;     ...
;         for (int tt = 0; tt < 32; ++tt) { const int r = t0 + tt;
;             const f32x4 h = ldx4(x, x16, (size_t)r * DM + c) * rs[15 + tt];
;             S += h;
;             const int tin = r - bstart; const float inv = 1.0f / (float)(tin + 1 < w ? tin + 1 : w);
;             const f32x4 p = (S * inv - h) * gv;
;             u32x2 o; o.x = pk2(p[0], p[1]); o.y = pk2(p[2], p[3]); *(u32x2*)(pooled + (size_t)r * DM + c) = o;
;             const int ro = r - w + 1; if (ro >= bstart) S -= ldx4(x, x16, (size_t)ro * DM + c) * rs[ro - (t0 - 15)]; }
.LplA_invd7:
	s_waitcnt vmcnt(22)
	v_mul_f32_e32 v52, s35, v140
	v_mul_f32_e32 v53, s35, v141
	v_mul_f32_e32 v54, s35, v142
	v_mul_f32_e32 v55, s35, v143
	v_fma_f32 v40, v140, s35, v40
	v_fma_f32 v41, v141, s35, v41
	v_fma_f32 v42, v142, s35, v42
	v_fma_f32 v43, v143, s35, v43
	v_fma_f32 v56, v38, v40, -v52
	v_fma_f32 v57, v38, v41, -v53
	v_fma_f32 v58, v38, v42, -v54
	v_fma_f32 v59, v38, v43, -v55
	v_mul_f32_e32 v56, v0, v56
	v_mul_f32_e32 v57, v1, v57
	v_mul_f32_e32 v58, v2, v58
	v_mul_f32_e32 v59, v3, v59
	v_cvt_pk_bf16_f32 v64, v56, v57
	v_cvt_pk_bf16_f32 v65, v58, v59
	s_add_i32 s34, s17, 7
	s_lshl_b32 s12, s34, 12
	v_lshl_add_u64 v[62:63], v[10:11], 0, s[12:13]
	global_store_dwordx2 v[62:63], v[64:65], off
	s_add_i32 s34, s28, 7
	s_cmp_lt_i32 s34, s44
	s_cbranch_scc1 .LplA_skip7
	s_add_i32 s37, s30, 7
	v_readlane_b32 s36, v37, s37
	s_waitcnt vmcnt(22)
	s_nop 1
	v_fma_f32 v40, -v144, s36, v40
	v_fma_f32 v41, -v145, s36, v41
	v_fma_f32 v42, -v146, s36, v42
	v_fma_f32 v43, -v147, s36, v43

; __device__ __forceinline__ unsigned pk2(float lo, float hi) { f32x2 v = {lo, hi}; bf16x2_t b = __builtin_convertvector(v, bf16x2_t); return __builtin_bit_cast(unsigned, b); }
; __device__ __forceinline__ float bflo(unsigned w) { return __uint_as_float(w << 16); }
; __device__ __forceinline__ float bfhi(unsigned w) { return __uint_as_float(w & 0xffff0000u); }
; __device__ __forceinline__ f32x4 ldx4(const float* x, const bf16_t* x16, size_t idx) {
;     if (x16) { const u32x2 w = *(const u32x2*)(x16 + idx); return (f32x4){bflo(w.x), bfhi(w.x), bflo(w.y), bfhi(w.y)}; }
;     return *(const f32x4*)(x + idx);
; __device__ __forceinline__ void pool_phase(const float* __restrict__ x, const bf16_t* __restrict__ x16, const float* __restrict__ g, const float* rsq, bf16_t* __restrict__ pooled, LAS unsigned char* lds, int tid, int wid, int lane, int bid) {
;     ...
;         __syncthreads();
;         const int c = tid * 4, w = 2 << (c >> 9);
;         const f32x4 gv = *(const f32x4*)(g + c);
;         f32x4 S = {0.f, 0.f, 0.f, 0.f};
;         for (int j = 1; j < w; ++j) { const int r = t0 - j; if (r >= bstart) S += ldx4(x, x16, (size_t)r * DM + c) * rs[15 - j]; }
;         for (int tt = 0; tt < 32; ++tt) { const int r = t0 + tt;
;             const f32x4 h = ldx4(x, x16, (size_t)r * DM + c) * rs[15 + tt];
;             S += h;
;             const int tin = r - bstart; const float inv = 1.0f / (float)(tin + 1 < w ? tin + 1 : w);
;             const f32x4 p = (S * inv - h) * gv;
;             u32x2 o; o.x = pk2(p[0], p[1]); o.y = pk2(p[2], p[3]); *(u32x2*)(pooled + (size_t)r * DM + c) = o;
;             const int ro = r - w + 1; if (ro >= bstart) S -= ldx4(x, x16, (size_t)ro * DM + c) * rs[ro - (t0 - 15)]; }
.LBB0_631:
	v_mov_b32_e32 v96, v97
	v_mov_b32_e32 v98, v97
	v_mov_b32_e32 v99, v97
	v_mov_b64_e32 v[4:5], v[96:97]
	v_mov_b64_e32 v[6:7], v[98:99]
	s_waitcnt vmcnt(0) lgkmcnt(0)
	s_barrier
	v_readfirstlane_b32 s17, v13
	v_lshlrev_b32_e32 v54, 2, v251
	v_min_u32_e32 v54, 0xb8, v54
	ds_read_b32 v23, v54
	s_mov_b32 s11, 0
	s_mov_b32 s26, s16
	s_sub_i32 s30, s16, s25
	s_sub_i32 s27, s16, s17
	s_add_i32 s27, s27, 1
	s_sub_i32 s29, 16, s17
	s_mov_b32 s28, 15
	v_mov_b32_e32 v24, 0
	v_mov_b32_e32 v25, 0
	v_mov_b32_e32 v26, 0
	v_mov_b32_e32 v27, 0
	v_cvt_f32_i32_e32 v29, s17
	v_div_scale_f32 v30, vcc, v29, v29, 1.0
	v_rcp_f32_e32 v31, v30
	v_div_scale_f32 v32, vcc, 1.0, v29, 1.0
	v_fma_f32 v33, -v30, v31, 1.0
	v_fmac_f32_e32 v31, v33, v31
	v_mul_f32_e32 v33, v32, v31
	v_fma_f32 v34, -v30, v33, v32
	v_fmac_f32_e32 v33, v34, v31
	v_fma_f32 v30, -v30, v33, v32
	v_div_fmas_f32 v30, v30, v31, v33
	v_div_fixup_f32 v55, v30, v29, 1.0
	s_sub_i32 s31, s16, 1
	s_max_i32 s31, s31, s25
	s_lshl_b32 s10, s31, 12
	v_lshl_add_u64 v[48:49], v[10:11], 0, s[10:11]
	global_load_dwordx2 v[132:133], v[48:49], off
	s_sub_i32 s31, s16, 2
	s_max_i32 s31, s31, s25
	s_lshl_b32 s10, s31, 12
	v_lshl_add_u64 v[48:49], v[10:11], 0, s[10:11]
	global_load_dwordx2 v[134:135], v[48:49], off
	s_sub_i32 s31, s16, 3
	s_max_i32 s31, s31, s25
	s_lshl_b32 s10, s31, 12
	v_lshl_add_u64 v[48:49], v[10:11], 0, s[10:11]
	global_load_dwordx2 v[136:137], v[48:49], off
	s_sub_i32 s31, s16, 4
	s_max_i32 s31, s31, s25
	s_lshl_b32 s10, s31, 12
	v_lshl_add_u64 v[48:49], v[10:11], 0, s[10:11]
	global_load_dwordx2 v[138:139], v[48:49], off
	s_sub_i32 s31, s16, 5
	s_max_i32 s31, s31, s25
	s_lshl_b32 s10, s31, 12
	v_lshl_add_u64 v[48:49], v[10:11], 0, s[10:11]
	global_load_dwordx2 v[140:141], v[48:49], off
	s_sub_i32 s31, s16, 6
	s_max_i32 s31, s31, s25
	s_lshl_b32 s10, s31, 12
	v_lshl_add_u64 v[48:49], v[10:11], 0, s[10:11]
	global_load_dwordx2 v[142:143], v[48:49], off
	s_sub_i32 s31, s16, 7
	s_max_i32 s31, s31, s25
	s_lshl_b32 s10, s31, 12
	v_lshl_add_u64 v[48:49], v[10:11], 0, s[10:11]
	global_load_dwordx2 v[144:145], v[48:49], off
	s_sub_i32 s31, s16, 8
	s_max_i32 s31, s31, s25
	s_lshl_b32 s10, s31, 12
	v_lshl_add_u64 v[48:49], v[10:11], 0, s[10:11]
	global_load_dwordx2 v[146:147], v[48:49], off
	s_sub_i32 s31, s16, 9
	s_max_i32 s31, s31, s25
	s_lshl_b32 s10, s31, 12
	v_lshl_add_u64 v[48:49], v[10:11], 0, s[10:11]
	global_load_dwordx2 v[148:149], v[48:49], off
	s_sub_i32 s31, s16, 10
	s_max_i32 s31, s31, s25
	s_lshl_b32 s10, s31, 12
	v_lshl_add_u64 v[48:49], v[10:11], 0, s[10:11]
	global_load_dwordx2 v[150:151], v[48:49], off
	s_sub_i32 s31, s16, 11
	s_max_i32 s31, s31, s25
	s_lshl_b32 s10, s31, 12
	v_lshl_add_u64 v[48:49], v[10:11], 0, s[10:11]
	global_load_dwordx2 v[152:153], v[48:49], off
	s_sub_i32 s31, s16, 12
	s_max_i32 s31, s31, s25
	s_lshl_b32 s10, s31, 12
	v_lshl_add_u64 v[48:49], v[10:11], 0, s[10:11]
	global_load_dwordx2 v[154:155], v[48:49], off
	s_sub_i32 s31, s16, 13
	s_max_i32 s31, s31, s25
	s_lshl_b32 s10, s31, 12
	v_lshl_add_u64 v[48:49], v[10:11], 0, s[10:11]
	global_load_dwordx2 v[156:157], v[48:49], off
	s_sub_i32 s31, s16, 14
	s_max_i32 s31, s31, s25
	s_lshl_b32 s10, s31, 12
	v_lshl_add_u64 v[48:49], v[10:11], 0, s[10:11]
	global_load_dwordx2 v[158:159], v[48:49], off
	s_sub_i32 s31, s16, 15
	s_max_i32 s31, s31, s25
	s_lshl_b32 s10, s31, 12
	v_lshl_add_u64 v[48:49], v[10:11], 0, s[10:11]
	global_load_dwordx2 v[160:161], v[48:49], off
	s_add_i32 s31, s26, 0
	s_lshl_b32 s10, s31, 12
	v_lshl_add_u64 v[48:49], v[10:11], 0, s[10:11]
	global_load_dwordx2 v[100:101], v[48:49], off
	s_add_i32 s31, s27, 0
	s_max_i32 s31, s31, s25
	s_lshl_b32 s10, s31, 12
	v_lshl_add_u64 v[48:49], v[10:11], 0, s[10:11]
	global_load_dwordx2 v[102:103], v[48:49], off
	s_add_i32 s31, s26, 1
	s_lshl_b32 s10, s31, 12
	v_lshl_add_u64 v[48:49], v[10:11], 0, s[10:11]
	global_load_dwordx2 v[104:105], v[48:49], off
	s_add_i32 s31, s27, 1
	s_max_i32 s31, s31, s25
	s_lshl_b32 s10, s31, 12
	v_lshl_add_u64 v[48:49], v[10:11], 0, s[10:11]
	global_load_dwordx2 v[106:107], v[48:49], off
	s_add_i32 s31, s26, 2
	s_lshl_b32 s10, s31, 12
	v_lshl_add_u64 v[48:49], v[10:11], 0, s[10:11]
	global_load_dwordx2 v[108:109], v[48:49], off
	s_add_i32 s31, s27, 2
	s_max_i32 s31, s31, s25
	s_lshl_b32 s10, s31, 12
	v_lshl_add_u64 v[48:49], v[10:11], 0, s[10:11]
	global_load_dwordx2 v[110:111], v[48:49], off
	s_add_i32 s31, s26, 3
	s_lshl_b32 s10, s31, 12
	v_lshl_add_u64 v[48:49], v[10:11], 0, s[10:11]
	global_load_dwordx2 v[112:113], v[48:49], off
	s_add_i32 s31, s27, 3
	s_max_i32 s31, s31, s25
	s_lshl_b32 s10, s31, 12
	v_lshl_add_u64 v[48:49], v[10:11], 0, s[10:11]
	global_load_dwordx2 v[114:115], v[48:49], off
	s_add_i32 s31, s26, 4
	s_lshl_b32 s10, s31, 12
	v_lshl_add_u64 v[48:49], v[10:11], 0, s[10:11]
	global_load_dwordx2 v[116:117], v[48:49], off
	s_add_i32 s31, s27, 4
	s_max_i32 s31, s31, s25
	s_lshl_b32 s10, s31, 12
	v_lshl_add_u64 v[48:49], v[10:11], 0, s[10:11]
	global_load_dwordx2 v[118:119], v[48:49], off
	s_add_i32 s31, s26, 5
	s_lshl_b32 s10, s31, 12
	v_lshl_add_u64 v[48:49], v[10:11], 0, s[10:11]
	global_load_dwordx2 v[120:121], v[48:49], off
	s_add_i32 s31, s27, 5
	s_max_i32 s31, s31, s25
	s_lshl_b32 s10, s31, 12
	v_lshl_add_u64 v[48:49], v[10:11], 0, s[10:11]
	global_load_dwordx2 v[122:123], v[48:49], off
	s_add_i32 s31, s26, 6
	s_lshl_b32 s10, s31, 12
	v_lshl_add_u64 v[48:49], v[10:11], 0, s[10:11]
	global_load_dwordx2 v[124:125], v[48:49], off
	s_add_i32 s31, s27, 6
	s_max_i32 s31, s31, s25
	s_lshl_b32 s10, s31, 12
	v_lshl_add_u64 v[48:49], v[10:11], 0, s[10:11]
	global_load_dwordx2 v[126:127], v[48:49], off
	s_add_i32 s31, s26, 7
	s_lshl_b32 s10, s31, 12
	v_lshl_add_u64 v[48:49], v[10:11], 0, s[10:11]
	global_load_dwordx2 v[128:129], v[48:49], off
	s_add_i32 s31, s27, 7
	s_max_i32 s31, s31, s25
	s_lshl_b32 s10, s31, 12
	v_lshl_add_u64 v[48:49], v[10:11], 0, s[10:11]
	global_load_dwordx2 v[130:131], v[48:49], off
	s_waitcnt lgkmcnt(0)
	s_cmp_le_i32 s17, 1
	s_cbranch_scc1 .LplB_init_done
; __device__ __forceinline__ float bflo(unsigned w) { return __uint_as_float(w << 16); }
; __device__ __forceinline__ float bfhi(unsigned w) { return __uint_as_float(w & 0xffff0000u); }
; __device__ __forceinline__ f32x4 ldx4(const float* x, const bf16_t* x16, size_t idx) {
;     if (x16) { const u32x2 w = *(const u32x2*)(x16 + idx); return (f32x4){bflo(w.x), bfhi(w.x), bflo(w.y), bfhi(w.y)}; }
;     return *(const f32x4*)(x + idx);
; __device__ __forceinline__ void pool_phase(const float* __restrict__ x, const bf16_t* __restrict__ x16, const float* __restrict__ g, const float* rsq, bf16_t* __restrict__ pooled, LAS unsigned char* lds, int tid, int wid, int lane, int bid) {
;     ...
;         f32x4 S = {0.f, 0.f, 0.f, 0.f};
;         for (int j = 1; j < w; ++j) { const int r = t0 - j; if (r >= bstart) S += ldx4(x, x16, (size_t)r * DM + c) * rs[15 - j]; }
	s_sub_i32 s31, s16, 1
	s_cmp_lt_i32 s31, s25
	s_cbranch_scc1 .LplB_init_done
	v_readlane_b32 s42, v23, 14
	s_waitcnt vmcnt(30)
	v_lshlrev_b32_e32 v44, 16, v132
	v_and_b32_e32 v45, 0xffff0000, v132
	v_lshlrev_b32_e32 v46, 16, v133
	v_and_b32_e32 v47, 0xffff0000, v133
	s_nop 1
	v_fma_f32 v24, v44, s42, v24
	v_fma_f32 v25, v45, s42, v25
	v_fma_f32 v26, v46, s42, v26
	v_fma_f32 v27, v47, s42, v27
	s_cmp_le_i32 s17, 2
	s_cbranch_scc1 .LplB_init_done
	s_sub_i32 s31, s16, 2
	s_cmp_lt_i32 s31, s25
	s_cbranch_scc1 .LplB_init_done
	v_readlane_b32 s42, v23, 13
	s_waitcnt vmcnt(29)
	v_lshlrev_b32_e32 v44, 16, v134
	v_and_b32_e32 v45, 0xffff0000, v134
	v_lshlrev_b32_e32 v46, 16, v135
	v_and_b32_e32 v47, 0xffff0000, v135
	s_nop 1
	v_fma_f32 v24, v44, s42, v24
	v_fma_f32 v25, v45, s42, v25
	v_fma_f32 v26, v46, s42, v26
	v_fma_f32 v27, v47, s42, v27
	s_cmp_le_i32 s17, 3
	s_cbranch_scc1 .LplB_init_done
	s_sub_i32 s31, s16, 3
	s_cmp_lt_i32 s31, s25
	s_cbranch_scc1 .LplB_init_done
	v_readlane_b32 s42, v23, 12
	s_waitcnt vmcnt(28)
	v_lshlrev_b32_e32 v44, 16, v136
	v_and_b32_e32 v45, 0xffff0000, v136
	v_lshlrev_b32_e32 v46, 16, v137
	v_and_b32_e32 v47, 0xffff0000, v137
	s_nop 1
	v_fma_f32 v24, v44, s42, v24
	v_fma_f32 v25, v45, s42, v25
	v_fma_f32 v26, v46, s42, v26
	v_fma_f32 v27, v47, s42, v27
	s_cmp_le_i32 s17, 4
	s_cbranch_scc1 .LplB_init_done
	s_sub_i32 s31, s16, 4
	s_cmp_lt_i32 s31, s25
	s_cbranch_scc1 .LplB_init_done
	v_readlane_b32 s42, v23, 11
	s_waitcnt vmcnt(27)
	v_lshlrev_b32_e32 v44, 16, v138
	v_and_b32_e32 v45, 0xffff0000, v138
	v_lshlrev_b32_e32 v46, 16, v139
	v_and_b32_e32 v47, 0xffff0000, v139
	s_nop 1
	v_fma_f32 v24, v44, s42, v24
	v_fma_f32 v25, v45, s42, v25
	v_fma_f32 v26, v46, s42, v26
	v_fma_f32 v27, v47, s42, v27
	s_cmp_le_i32 s17, 5
	s_cbranch_scc1 .LplB_init_done
	s_sub_i32 s31, s16, 5
	s_cmp_lt_i32 s31, s25
	s_cbranch_scc1 .LplB_init_done
	v_readlane_b32 s42, v23, 10
	s_waitcnt vmcnt(26)
	v_lshlrev_b32_e32 v44, 16, v140
	v_and_b32_e32 v45, 0xffff0000, v140
	v_lshlrev_b32_e32 v46, 16, v141
	v_and_b32_e32 v47, 0xffff0000, v141
	s_nop 1
	v_fma_f32 v24, v44, s42, v24
	v_fma_f32 v25, v45, s42, v25
	v_fma_f32 v26, v46, s42, v26
	v_fma_f32 v27, v47, s42, v27
	s_cmp_le_i32 s17, 6
	s_cbranch_scc1 .LplB_init_done
	s_sub_i32 s31, s16, 6
	s_cmp_lt_i32 s31, s25
	s_cbranch_scc1 .LplB_init_done
	v_readlane_b32 s42, v23, 9
	s_waitcnt vmcnt(25)
	v_lshlrev_b32_e32 v44, 16, v142
	v_and_b32_e32 v45, 0xffff0000, v142
	v_lshlrev_b32_e32 v46, 16, v143
	v_and_b32_e32 v47, 0xffff0000, v143
	s_nop 1
	v_fma_f32 v24, v44, s42, v24
	v_fma_f32 v25, v45, s42, v25
	v_fma_f32 v26, v46, s42, v26
	v_fma_f32 v27, v47, s42, v27
	s_cmp_le_i32 s17, 7
	s_cbranch_scc1 .LplB_init_done
	s_sub_i32 s31, s16, 7
	s_cmp_lt_i32 s31, s25
	s_cbranch_scc1 .LplB_init_done
	v_readlane_b32 s42, v23, 8
	s_waitcnt vmcnt(24)
	v_lshlrev_b32_e32 v44, 16, v144
	v_and_b32_e32 v45, 0xffff0000, v144
	v_lshlrev_b32_e32 v46, 16, v145
	v_and_b32_e32 v47, 0xffff0000, v145
	s_nop 1
	v_fma_f32 v24, v44, s42, v24
	v_fma_f32 v25, v45, s42, v25
	v_fma_f32 v26, v46, s42, v26
	v_fma_f32 v27, v47, s42, v27
	s_cmp_le_i32 s17, 8
	s_cbranch_scc1 .LplB_init_done
	s_sub_i32 s31, s16, 8
	s_cmp_lt_i32 s31, s25
	s_cbranch_scc1 .LplB_init_done
	v_readlane_b32 s42, v23, 7
	s_waitcnt vmcnt(23)
	v_lshlrev_b32_e32 v44, 16, v146
	v_and_b32_e32 v45, 0xffff0000, v146
	v_lshlrev_b32_e32 v46, 16, v147
	v_and_b32_e32 v47, 0xffff0000, v147
	s_nop 1
	v_fma_f32 v24, v44, s42, v24
	v_fma_f32 v25, v45, s42, v25
	v_fma_f32 v26, v46, s42, v26
	v_fma_f32 v27, v47, s42, v27
	s_cmp_le_i32 s17, 9
	s_cbranch_scc1 .LplB_init_done
	s_sub_i32 s31, s16, 9
	s_cmp_lt_i32 s31, s25
	s_cbranch_scc1 .LplB_init_done
	v_readlane_b32 s42, v23, 6
	s_waitcnt vmcnt(22)
	v_lshlrev_b32_e32 v44, 16, v148
	v_and_b32_e32 v45, 0xffff0000, v148
	v_lshlrev_b32_e32 v46, 16, v149
	v_and_b32_e32 v47, 0xffff0000, v149
	s_nop 1
	v_fma_f32 v24, v44, s42, v24
	v_fma_f32 v25, v45, s42, v25
	v_fma_f32 v26, v46, s42, v26
	v_fma_f32 v27, v47, s42, v27
	s_cmp_le_i32 s17, 10
	s_cbranch_scc1 .LplB_init_done
	s_sub_i32 s31, s16, 10
	s_cmp_lt_i32 s31, s25
	s_cbranch_scc1 .LplB_init_done
	v_readlane_b32 s42, v23, 5
	s_waitcnt vmcnt(21)
	v_lshlrev_b32_e32 v44, 16, v150
	v_and_b32_e32 v45, 0xffff0000, v150
	v_lshlrev_b32_e32 v46, 16, v151
	v_and_b32_e32 v47, 0xffff0000, v151
	s_nop 1
	v_fma_f32 v24, v44, s42, v24
	v_fma_f32 v25, v45, s42, v25
	v_fma_f32 v26, v46, s42, v26
	v_fma_f32 v27, v47, s42, v27
	s_cmp_le_i32 s17, 11
	s_cbranch_scc1 .LplB_init_done
	s_sub_i32 s31, s16, 11
	s_cmp_lt_i32 s31, s25
	s_cbranch_scc1 .LplB_init_done
	v_readlane_b32 s42, v23, 4
	s_waitcnt vmcnt(20)
	v_lshlrev_b32_e32 v44, 16, v152
	v_and_b32_e32 v45, 0xffff0000, v152
	v_lshlrev_b32_e32 v46, 16, v153
	v_and_b32_e32 v47, 0xffff0000, v153
	s_nop 1
	v_fma_f32 v24, v44, s42, v24
	v_fma_f32 v25, v45, s42, v25
	v_fma_f32 v26, v46, s42, v26
	v_fma_f32 v27, v47, s42, v27
	s_cmp_le_i32 s17, 12
	s_cbranch_scc1 .LplB_init_done
	s_sub_i32 s31, s16, 12
	s_cmp_lt_i32 s31, s25
	s_cbranch_scc1 .LplB_init_done
	v_readlane_b32 s42, v23, 3
	s_waitcnt vmcnt(19)
	v_lshlrev_b32_e32 v44, 16, v154
	v_and_b32_e32 v45, 0xffff0000, v154
	v_lshlrev_b32_e32 v46, 16, v155
	v_and_b32_e32 v47, 0xffff0000, v155
	s_nop 1
	v_fma_f32 v24, v44, s42, v24
	v_fma_f32 v25, v45, s42, v25
	v_fma_f32 v26, v46, s42, v26
	v_fma_f32 v27, v47, s42, v27
	s_cmp_le_i32 s17, 13
	s_cbranch_scc1 .LplB_init_done
	s_sub_i32 s31, s16, 13
	s_cmp_lt_i32 s31, s25
	s_cbranch_scc1 .LplB_init_done
	v_readlane_b32 s42, v23, 2
	s_waitcnt vmcnt(18)
	v_lshlrev_b32_e32 v44, 16, v156
	v_and_b32_e32 v45, 0xffff0000, v156
	v_lshlrev_b32_e32 v46, 16, v157
	v_and_b32_e32 v47, 0xffff0000, v157
	s_nop 1
	v_fma_f32 v24, v44, s42, v24
	v_fma_f32 v25, v45, s42, v25
	v_fma_f32 v26, v46, s42, v26
	v_fma_f32 v27, v47, s42, v27
	s_cmp_le_i32 s17, 14
	s_cbranch_scc1 .LplB_init_done
	s_sub_i32 s31, s16, 14
	s_cmp_lt_i32 s31, s25
	s_cbranch_scc1 .LplB_init_done
	v_readlane_b32 s42, v23, 1
	s_waitcnt vmcnt(17)
	v_lshlrev_b32_e32 v44, 16, v158
	v_and_b32_e32 v45, 0xffff0000, v158
	v_lshlrev_b32_e32 v46, 16, v159
	v_and_b32_e32 v47, 0xffff0000, v159
	s_nop 1
	v_fma_f32 v24, v44, s42, v24
	v_fma_f32 v25, v45, s42, v25
	v_fma_f32 v26, v46, s42, v26
	v_fma_f32 v27, v47, s42, v27
	s_cmp_le_i32 s17, 15
	s_cbranch_scc1 .LplB_init_done
	s_sub_i32 s31, s16, 15
	s_cmp_lt_i32 s31, s25
	s_cbranch_scc1 .LplB_init_done
	v_readlane_b32 s42, v23, 0
	s_waitcnt vmcnt(16)
	v_lshlrev_b32_e32 v44, 16, v160
	v_and_b32_e32 v45, 0xffff0000, v160
	v_lshlrev_b32_e32 v46, 16, v161
	v_and_b32_e32 v47, 0xffff0000, v161
	s_nop 1
	v_fma_f32 v24, v44, s42, v24
	v_fma_f32 v25, v45, s42, v25
	v_fma_f32 v26, v46, s42, v26
	v_fma_f32 v27, v47, s42, v27
; __device__ __forceinline__ unsigned pk2(float lo, float hi) { f32x2 v = {lo, hi}; bf16x2_t b = __builtin_convertvector(v, bf16x2_t); return __builtin_bit_cast(unsigned, b); }
; __device__ __forceinline__ float bflo(unsigned w) { return __uint_as_float(w << 16); }
; __device__ __forceinline__ float bfhi(unsigned w) { return __uint_as_float(w & 0xffff0000u); }
; __device__ __forceinline__ f32x4 ldx4(const float* x, const bf16_t* x16, size_t idx) {
;     if (x16) { const u32x2 w = *(const u32x2*)(x16 + idx); return (f32x4){bflo(w.x), bfhi(w.x), bflo(w.y), bfhi(w.y)}; }
;     return *(const f32x4*)(x + idx);
; __device__ __forceinline__ void pool_phase(const float* __restrict__ x, const bf16_t* __restrict__ x16, const float* __restrict__ g, const float* rsq, bf16_t* __restrict__ pooled, LAS unsigned char* lds, int tid, int wid, int lane, int bid) {
;     ...
;         for (int tt = 0; tt < 32; ++tt) { const int r = t0 + tt;
;             const f32x4 h = ldx4(x, x16, (size_t)r * DM + c) * rs[15 + tt];
;             S += h;
;             const int tin = r - bstart; const float inv = 1.0f / (float)(tin + 1 < w ? tin + 1 : w);
;             const f32x4 p = (S * inv - h) * gv;
;             u32x2 o; o.x = pk2(p[0], p[1]); o.y = pk2(p[2], p[3]); *(u32x2*)(pooled + (size_t)r * DM + c) = o;
;             const int ro = r - w + 1; if (ro >= bstart) S -= ldx4(x, x16, (size_t)ro * DM + c) * rs[ro - (t0 - 15)]; }
.LplB_init_done:
.LplB_loop:
	s_add_i32 s53, s28, 0
	v_readlane_b32 s42, v23, s53
	s_add_i32 s31, s30, 1
	s_cmp_ge_i32 s31, s17
	s_cbranch_scc1 .LplB_invw0
	v_cvt_f32_i32_e32 v29, s31
	v_div_scale_f32 v30, vcc, v29, v29, 1.0
	v_rcp_f32_e32 v31, v30
	v_div_scale_f32 v32, vcc, 1.0, v29, 1.0
	v_fma_f32 v33, -v30, v31, 1.0
	v_fmac_f32_e32 v31, v33, v31
	v_mul_f32_e32 v33, v32, v31
	v_fma_f32 v34, -v30, v33, v32
	v_fmac_f32_e32 v33, v34, v31
	v_fma_f32 v30, -v30, v33, v32
	v_div_fmas_f32 v30, v30, v31, v33
	v_div_fixup_f32 v28, v30, v29, 1.0
	s_branch .LplB_invd0
.LplB_invw0:
	v_mov_b32_e32 v28, v55
.LplB_invd0:
	s_waitcnt vmcnt(15)
	v_lshlrev_b32_e32 v44, 16, v100
	v_and_b32_e32 v45, 0xffff0000, v100
	v_lshlrev_b32_e32 v46, 16, v101
	v_and_b32_e32 v47, 0xffff0000, v101
	v_mul_f32_e32 v36, s42, v44
	v_mul_f32_e32 v37, s42, v45
	v_mul_f32_e32 v38, s42, v46
	v_mul_f32_e32 v39, s42, v47
	v_fma_f32 v24, v44, s42, v24
	v_fma_f32 v25, v45, s42, v25
	v_fma_f32 v26, v46, s42, v26
	v_fma_f32 v27, v47, s42, v27
	v_fma_f32 v40, v28, v24, -v36
	v_fma_f32 v41, v28, v25, -v37
	v_fma_f32 v42, v28, v26, -v38
	v_fma_f32 v43, v28, v27, -v39
	v_mul_f32_e32 v40, v0, v40
	v_mul_f32_e32 v41, v1, v41
	v_mul_f32_e32 v42, v2, v42
	v_mul_f32_e32 v43, v3, v43
	v_cvt_pk_bf16_f32 v52, v40, v41
	v_cvt_pk_bf16_f32 v53, v42, v43
	s_add_i32 s31, s26, 0
	s_lshl_b32 s10, s31, 12
	v_lshl_add_u64 v[50:51], v[8:9], 0, s[10:11]
	global_store_dwordx2 v[50:51], v[52:53], off
	s_add_i32 s31, s27, 0
	s_cmp_lt_i32 s31, s25
	s_cbranch_scc1 .LplB_skip0
	s_add_i32 s53, s29, 0
	v_readlane_b32 s43, v23, s53
	s_waitcnt vmcnt(15)
	v_lshlrev_b32_e32 v44, 16, v102
	v_and_b32_e32 v45, 0xffff0000, v102
	v_lshlrev_b32_e32 v46, 16, v103
	v_and_b32_e32 v47, 0xffff0000, v103
	s_nop 1
	v_fma_f32 v24, -v44, s43, v24
	v_fma_f32 v25, -v45, s43, v25
	v_fma_f32 v26, -v46, s43, v26
	v_fma_f32 v27, -v47, s43, v27
.LplB_skip0:
	s_add_i32 s31, s26, 8
	s_min_i32 s31, s31, 0x1fff
	s_lshl_b32 s10, s31, 12
	v_lshl_add_u64 v[48:49], v[10:11], 0, s[10:11]
	global_load_dwordx2 v[100:101], v[48:49], off
	s_add_i32 s31, s27, 8
	s_max_i32 s31, s31, s25
	s_min_i32 s31, s31, 0x1fff
	s_lshl_b32 s10, s31, 12
	v_lshl_add_u64 v[48:49], v[10:11], 0, s[10:11]
	global_load_dwordx2 v[102:103], v[48:49], off
	s_add_i32 s53, s28, 1
	v_readlane_b32 s42, v23, s53
	s_add_i32 s31, s30, 2
	s_cmp_ge_i32 s31, s17
	s_cbranch_scc1 .LplB_invw1
	v_cvt_f32_i32_e32 v29, s31
	v_div_scale_f32 v30, vcc, v29, v29, 1.0
	v_rcp_f32_e32 v31, v30
	v_div_scale_f32 v32, vcc, 1.0, v29, 1.0
	v_fma_f32 v33, -v30, v31, 1.0
	v_fmac_f32_e32 v31, v33, v31
	v_mul_f32_e32 v33, v32, v31
	v_fma_f32 v34, -v30, v33, v32
	v_fmac_f32_e32 v33, v34, v31
	v_fma_f32 v30, -v30, v33, v32
	v_div_fmas_f32 v30, v30, v31, v33
	v_div_fixup_f32 v28, v30, v29, 1.0
	s_branch .LplB_invd1

; __device__ __forceinline__ unsigned pk2(float lo, float hi) { f32x2 v = {lo, hi}; bf16x2_t b = __builtin_convertvector(v, bf16x2_t); return __builtin_bit_cast(unsigned, b); }
; __device__ __forceinline__ float bflo(unsigned w) { return __uint_as_float(w << 16); }
; __device__ __forceinline__ float bfhi(unsigned w) { return __uint_as_float(w & 0xffff0000u); }
; __device__ __forceinline__ f32x4 ldx4(const float* x, const bf16_t* x16, size_t idx) {
;     if (x16) { const u32x2 w = *(const u32x2*)(x16 + idx); return (f32x4){bflo(w.x), bfhi(w.x), bflo(w.y), bfhi(w.y)}; }
;     return *(const f32x4*)(x + idx);
; __device__ __forceinline__ void pool_phase(const float* __restrict__ x, const bf16_t* __restrict__ x16, const float* __restrict__ g, const float* rsq, bf16_t* __restrict__ pooled, LAS unsigned char* lds, int tid, int wid, int lane, int bid) {
;     ...
;         for (int tt = 0; tt < 32; ++tt) { const int r = t0 + tt;
;             const f32x4 h = ldx4(x, x16, (size_t)r * DM + c) * rs[15 + tt];
;             S += h;
;             const int tin = r - bstart; const float inv = 1.0f / (float)(tin + 1 < w ? tin + 1 : w);
;             const f32x4 p = (S * inv - h) * gv;
;             u32x2 o; o.x = pk2(p[0], p[1]); o.y = pk2(p[2], p[3]); *(u32x2*)(pooled + (size_t)r * DM + c) = o;
;             const int ro = r - w + 1; if (ro >= bstart) S -= ldx4(x, x16, (size_t)ro * DM + c) * rs[ro - (t0 - 15)]; }
.LplB_invd1:
	s_waitcnt vmcnt(16)
	v_lshlrev_b32_e32 v44, 16, v104
	v_and_b32_e32 v45, 0xffff0000, v104
	v_lshlrev_b32_e32 v46, 16, v105
	v_and_b32_e32 v47, 0xffff0000, v105
	v_mul_f32_e32 v36, s42, v44
	v_mul_f32_e32 v37, s42, v45
	v_mul_f32_e32 v38, s42, v46
	v_mul_f32_e32 v39, s42, v47
	v_fma_f32 v24, v44, s42, v24
	v_fma_f32 v25, v45, s42, v25
	v_fma_f32 v26, v46, s42, v26
	v_fma_f32 v27, v47, s42, v27
	v_fma_f32 v40, v28, v24, -v36
	v_fma_f32 v41, v28, v25, -v37
	v_fma_f32 v42, v28, v26, -v38
	v_fma_f32 v43, v28, v27, -v39
	v_mul_f32_e32 v40, v0, v40
	v_mul_f32_e32 v41, v1, v41
	v_mul_f32_e32 v42, v2, v42
	v_mul_f32_e32 v43, v3, v43
	v_cvt_pk_bf16_f32 v52, v40, v41
	v_cvt_pk_bf16_f32 v53, v42, v43
	s_add_i32 s31, s26, 1
	s_lshl_b32 s10, s31, 12
	v_lshl_add_u64 v[50:51], v[8:9], 0, s[10:11]
	global_store_dwordx2 v[50:51], v[52:53], off
	s_add_i32 s31, s27, 1
	s_cmp_lt_i32 s31, s25
	s_cbranch_scc1 .LplB_skip1
	s_add_i32 s53, s29, 1
	v_readlane_b32 s43, v23, s53
	s_waitcnt vmcnt(16)
	v_lshlrev_b32_e32 v44, 16, v106
	v_and_b32_e32 v45, 0xffff0000, v106
	v_lshlrev_b32_e32 v46, 16, v107
	v_and_b32_e32 v47, 0xffff0000, v107
	s_nop 1
	v_fma_f32 v24, -v44, s43, v24
	v_fma_f32 v25, -v45, s43, v25
	v_fma_f32 v26, -v46, s43, v26
	v_fma_f32 v27, -v47, s43, v27
.LplB_skip1:
	s_add_i32 s31, s26, 9
	s_min_i32 s31, s31, 0x1fff
	s_lshl_b32 s10, s31, 12
	v_lshl_add_u64 v[48:49], v[10:11], 0, s[10:11]
	global_load_dwordx2 v[104:105], v[48:49], off
	s_add_i32 s31, s27, 9
	s_max_i32 s31, s31, s25
	s_min_i32 s31, s31, 0x1fff
	s_lshl_b32 s10, s31, 12
	v_lshl_add_u64 v[48:49], v[10:11], 0, s[10:11]
	global_load_dwordx2 v[106:107], v[48:49], off
	s_add_i32 s53, s28, 2
	v_readlane_b32 s42, v23, s53
	s_add_i32 s31, s30, 3
	s_cmp_ge_i32 s31, s17
	s_cbranch_scc1 .LplB_invw2
	v_cvt_f32_i32_e32 v29, s31
	v_div_scale_f32 v30, vcc, v29, v29, 1.0
	v_rcp_f32_e32 v31, v30
	v_div_scale_f32 v32, vcc, 1.0, v29, 1.0
	v_fma_f32 v33, -v30, v31, 1.0
	v_fmac_f32_e32 v31, v33, v31
	v_mul_f32_e32 v33, v32, v31
	v_fma_f32 v34, -v30, v33, v32
	v_fmac_f32_e32 v33, v34, v31
	v_fma_f32 v30, -v30, v33, v32
	v_div_fmas_f32 v30, v30, v31, v33
	v_div_fixup_f32 v28, v30, v29, 1.0
	s_branch .LplB_invd2

; __device__ __forceinline__ unsigned pk2(float lo, float hi) { f32x2 v = {lo, hi}; bf16x2_t b = __builtin_convertvector(v, bf16x2_t); return __builtin_bit_cast(unsigned, b); }
; __device__ __forceinline__ float bflo(unsigned w) { return __uint_as_float(w << 16); }
; __device__ __forceinline__ float bfhi(unsigned w) { return __uint_as_float(w & 0xffff0000u); }
; __device__ __forceinline__ f32x4 ldx4(const float* x, const bf16_t* x16, size_t idx) {
;     if (x16) { const u32x2 w = *(const u32x2*)(x16 + idx); return (f32x4){bflo(w.x), bfhi(w.x), bflo(w.y), bfhi(w.y)}; }
;     return *(const f32x4*)(x + idx);
; __device__ __forceinline__ void pool_phase(const float* __restrict__ x, const bf16_t* __restrict__ x16, const float* __restrict__ g, const float* rsq, bf16_t* __restrict__ pooled, LAS unsigned char* lds, int tid, int wid, int lane, int bid) {
;     ...
;         for (int tt = 0; tt < 32; ++tt) { const int r = t0 + tt;
;             const f32x4 h = ldx4(x, x16, (size_t)r * DM + c) * rs[15 + tt];
;             S += h;
;             const int tin = r - bstart; const float inv = 1.0f / (float)(tin + 1 < w ? tin + 1 : w);
;             const f32x4 p = (S * inv - h) * gv;
;             u32x2 o; o.x = pk2(p[0], p[1]); o.y = pk2(p[2], p[3]); *(u32x2*)(pooled + (size_t)r * DM + c) = o;
;             const int ro = r - w + 1; if (ro >= bstart) S -= ldx4(x, x16, (size_t)ro * DM + c) * rs[ro - (t0 - 15)]; }
.LplB_invd2:
	s_waitcnt vmcnt(17)
	v_lshlrev_b32_e32 v44, 16, v108
	v_and_b32_e32 v45, 0xffff0000, v108
	v_lshlrev_b32_e32 v46, 16, v109
	v_and_b32_e32 v47, 0xffff0000, v109
	v_mul_f32_e32 v36, s42, v44
	v_mul_f32_e32 v37, s42, v45
	v_mul_f32_e32 v38, s42, v46
	v_mul_f32_e32 v39, s42, v47
	v_fma_f32 v24, v44, s42, v24
	v_fma_f32 v25, v45, s42, v25
	v_fma_f32 v26, v46, s42, v26
	v_fma_f32 v27, v47, s42, v27
	v_fma_f32 v40, v28, v24, -v36
	v_fma_f32 v41, v28, v25, -v37
	v_fma_f32 v42, v28, v26, -v38
	v_fma_f32 v43, v28, v27, -v39
	v_mul_f32_e32 v40, v0, v40
	v_mul_f32_e32 v41, v1, v41
	v_mul_f32_e32 v42, v2, v42
	v_mul_f32_e32 v43, v3, v43
	v_cvt_pk_bf16_f32 v52, v40, v41
	v_cvt_pk_bf16_f32 v53, v42, v43
	s_add_i32 s31, s26, 2
	s_lshl_b32 s10, s31, 12
	v_lshl_add_u64 v[50:51], v[8:9], 0, s[10:11]
	global_store_dwordx2 v[50:51], v[52:53], off
	s_add_i32 s31, s27, 2
	s_cmp_lt_i32 s31, s25
	s_cbranch_scc1 .LplB_skip2
	s_add_i32 s53, s29, 2
	v_readlane_b32 s43, v23, s53
	s_waitcnt vmcnt(17)
	v_lshlrev_b32_e32 v44, 16, v110
	v_and_b32_e32 v45, 0xffff0000, v110
	v_lshlrev_b32_e32 v46, 16, v111
	v_and_b32_e32 v47, 0xffff0000, v111
	s_nop 1
	v_fma_f32 v24, -v44, s43, v24
	v_fma_f32 v25, -v45, s43, v25
	v_fma_f32 v26, -v46, s43, v26
	v_fma_f32 v27, -v47, s43, v27
.LplB_skip2:
	s_add_i32 s31, s26, 10
	s_min_i32 s31, s31, 0x1fff
	s_lshl_b32 s10, s31, 12
	v_lshl_add_u64 v[48:49], v[10:11], 0, s[10:11]
	global_load_dwordx2 v[108:109], v[48:49], off
	s_add_i32 s31, s27, 10
	s_max_i32 s31, s31, s25
	s_min_i32 s31, s31, 0x1fff
	s_lshl_b32 s10, s31, 12
	v_lshl_add_u64 v[48:49], v[10:11], 0, s[10:11]
	global_load_dwordx2 v[110:111], v[48:49], off
	s_add_i32 s53, s28, 3
	v_readlane_b32 s42, v23, s53
	s_add_i32 s31, s30, 4
	s_cmp_ge_i32 s31, s17
	s_cbranch_scc1 .LplB_invw3
	v_cvt_f32_i32_e32 v29, s31
	v_div_scale_f32 v30, vcc, v29, v29, 1.0
	v_rcp_f32_e32 v31, v30
	v_div_scale_f32 v32, vcc, 1.0, v29, 1.0
	v_fma_f32 v33, -v30, v31, 1.0
	v_fmac_f32_e32 v31, v33, v31
	v_mul_f32_e32 v33, v32, v31
	v_fma_f32 v34, -v30, v33, v32
	v_fmac_f32_e32 v33, v34, v31
	v_fma_f32 v30, -v30, v33, v32
	v_div_fmas_f32 v30, v30, v31, v33
	v_div_fixup_f32 v28, v30, v29, 1.0
	s_branch .LplB_invd3

; __device__ __forceinline__ unsigned pk2(float lo, float hi) { f32x2 v = {lo, hi}; bf16x2_t b = __builtin_convertvector(v, bf16x2_t); return __builtin_bit_cast(unsigned, b); }
; __device__ __forceinline__ float bflo(unsigned w) { return __uint_as_float(w << 16); }
; __device__ __forceinline__ float bfhi(unsigned w) { return __uint_as_float(w & 0xffff0000u); }
; __device__ __forceinline__ f32x4 ldx4(const float* x, const bf16_t* x16, size_t idx) {
;     if (x16) { const u32x2 w = *(const u32x2*)(x16 + idx); return (f32x4){bflo(w.x), bfhi(w.x), bflo(w.y), bfhi(w.y)}; }
;     return *(const f32x4*)(x + idx);
; __device__ __forceinline__ void pool_phase(const float* __restrict__ x, const bf16_t* __restrict__ x16, const float* __restrict__ g, const float* rsq, bf16_t* __restrict__ pooled, LAS unsigned char* lds, int tid, int wid, int lane, int bid) {
;     ...
;         for (int tt = 0; tt < 32; ++tt) { const int r = t0 + tt;
;             const f32x4 h = ldx4(x, x16, (size_t)r * DM + c) * rs[15 + tt];
;             S += h;
;             const int tin = r - bstart; const float inv = 1.0f / (float)(tin + 1 < w ? tin + 1 : w);
;             const f32x4 p = (S * inv - h) * gv;
;             u32x2 o; o.x = pk2(p[0], p[1]); o.y = pk2(p[2], p[3]); *(u32x2*)(pooled + (size_t)r * DM + c) = o;
;             const int ro = r - w + 1; if (ro >= bstart) S -= ldx4(x, x16, (size_t)ro * DM + c) * rs[ro - (t0 - 15)]; }
.LplB_invd3:
	s_waitcnt vmcnt(18)
	v_lshlrev_b32_e32 v44, 16, v112
	v_and_b32_e32 v45, 0xffff0000, v112
	v_lshlrev_b32_e32 v46, 16, v113
	v_and_b32_e32 v47, 0xffff0000, v113
	v_mul_f32_e32 v36, s42, v44
	v_mul_f32_e32 v37, s42, v45
	v_mul_f32_e32 v38, s42, v46
	v_mul_f32_e32 v39, s42, v47
	v_fma_f32 v24, v44, s42, v24
	v_fma_f32 v25, v45, s42, v25
	v_fma_f32 v26, v46, s42, v26
	v_fma_f32 v27, v47, s42, v27
	v_fma_f32 v40, v28, v24, -v36
	v_fma_f32 v41, v28, v25, -v37
	v_fma_f32 v42, v28, v26, -v38
	v_fma_f32 v43, v28, v27, -v39
	v_mul_f32_e32 v40, v0, v40
	v_mul_f32_e32 v41, v1, v41
	v_mul_f32_e32 v42, v2, v42
	v_mul_f32_e32 v43, v3, v43
	v_cvt_pk_bf16_f32 v52, v40, v41
	v_cvt_pk_bf16_f32 v53, v42, v43
	s_add_i32 s31, s26, 3
	s_lshl_b32 s10, s31, 12
	v_lshl_add_u64 v[50:51], v[8:9], 0, s[10:11]
	global_store_dwordx2 v[50:51], v[52:53], off
	s_add_i32 s31, s27, 3
	s_cmp_lt_i32 s31, s25
	s_cbranch_scc1 .LplB_skip3
	s_add_i32 s53, s29, 3
	v_readlane_b32 s43, v23, s53
	s_waitcnt vmcnt(18)
	v_lshlrev_b32_e32 v44, 16, v114
	v_and_b32_e32 v45, 0xffff0000, v114
	v_lshlrev_b32_e32 v46, 16, v115
	v_and_b32_e32 v47, 0xffff0000, v115
	s_nop 1
	v_fma_f32 v24, -v44, s43, v24
	v_fma_f32 v25, -v45, s43, v25
	v_fma_f32 v26, -v46, s43, v26
	v_fma_f32 v27, -v47, s43, v27
.LplB_skip3:
	s_add_i32 s31, s26, 11
	s_min_i32 s31, s31, 0x1fff
	s_lshl_b32 s10, s31, 12
	v_lshl_add_u64 v[48:49], v[10:11], 0, s[10:11]
	global_load_dwordx2 v[112:113], v[48:49], off
	s_add_i32 s31, s27, 11
	s_max_i32 s31, s31, s25
	s_min_i32 s31, s31, 0x1fff
	s_lshl_b32 s10, s31, 12
	v_lshl_add_u64 v[48:49], v[10:11], 0, s[10:11]
	global_load_dwordx2 v[114:115], v[48:49], off
	s_add_i32 s53, s28, 4
	v_readlane_b32 s42, v23, s53
	s_add_i32 s31, s30, 5
	s_cmp_ge_i32 s31, s17
	s_cbranch_scc1 .LplB_invw4
	v_cvt_f32_i32_e32 v29, s31
	v_div_scale_f32 v30, vcc, v29, v29, 1.0
	v_rcp_f32_e32 v31, v30
	v_div_scale_f32 v32, vcc, 1.0, v29, 1.0
	v_fma_f32 v33, -v30, v31, 1.0
	v_fmac_f32_e32 v31, v33, v31
	v_mul_f32_e32 v33, v32, v31
	v_fma_f32 v34, -v30, v33, v32
	v_fmac_f32_e32 v33, v34, v31
	v_fma_f32 v30, -v30, v33, v32
	v_div_fmas_f32 v30, v30, v31, v33
	v_div_fixup_f32 v28, v30, v29, 1.0
	s_branch .LplB_invd4

; __device__ __forceinline__ unsigned pk2(float lo, float hi) { f32x2 v = {lo, hi}; bf16x2_t b = __builtin_convertvector(v, bf16x2_t); return __builtin_bit_cast(unsigned, b); }
; __device__ __forceinline__ float bflo(unsigned w) { return __uint_as_float(w << 16); }
; __device__ __forceinline__ float bfhi(unsigned w) { return __uint_as_float(w & 0xffff0000u); }
; __device__ __forceinline__ f32x4 ldx4(const float* x, const bf16_t* x16, size_t idx) {
;     if (x16) { const u32x2 w = *(const u32x2*)(x16 + idx); return (f32x4){bflo(w.x), bfhi(w.x), bflo(w.y), bfhi(w.y)}; }
;     return *(const f32x4*)(x + idx);
; __device__ __forceinline__ void pool_phase(const float* __restrict__ x, const bf16_t* __restrict__ x16, const float* __restrict__ g, const float* rsq, bf16_t* __restrict__ pooled, LAS unsigned char* lds, int tid, int wid, int lane, int bid) {
;     ...
;         for (int tt = 0; tt < 32; ++tt) { const int r = t0 + tt;
;             const f32x4 h = ldx4(x, x16, (size_t)r * DM + c) * rs[15 + tt];
;             S += h;
;             const int tin = r - bstart; const float inv = 1.0f / (float)(tin + 1 < w ? tin + 1 : w);
;             const f32x4 p = (S * inv - h) * gv;
;             u32x2 o; o.x = pk2(p[0], p[1]); o.y = pk2(p[2], p[3]); *(u32x2*)(pooled + (size_t)r * DM + c) = o;
;             const int ro = r - w + 1; if (ro >= bstart) S -= ldx4(x, x16, (size_t)ro * DM + c) * rs[ro - (t0 - 15)]; }
.LplB_invd4:
	s_waitcnt vmcnt(19)
	v_lshlrev_b32_e32 v44, 16, v116
	v_and_b32_e32 v45, 0xffff0000, v116
	v_lshlrev_b32_e32 v46, 16, v117
	v_and_b32_e32 v47, 0xffff0000, v117
	v_mul_f32_e32 v36, s42, v44
	v_mul_f32_e32 v37, s42, v45
	v_mul_f32_e32 v38, s42, v46
	v_mul_f32_e32 v39, s42, v47
	v_fma_f32 v24, v44, s42, v24
	v_fma_f32 v25, v45, s42, v25
	v_fma_f32 v26, v46, s42, v26
	v_fma_f32 v27, v47, s42, v27
	v_fma_f32 v40, v28, v24, -v36
	v_fma_f32 v41, v28, v25, -v37
	v_fma_f32 v42, v28, v26, -v38
	v_fma_f32 v43, v28, v27, -v39
	v_mul_f32_e32 v40, v0, v40
	v_mul_f32_e32 v41, v1, v41
	v_mul_f32_e32 v42, v2, v42
	v_mul_f32_e32 v43, v3, v43
	v_cvt_pk_bf16_f32 v52, v40, v41
	v_cvt_pk_bf16_f32 v53, v42, v43
	s_add_i32 s31, s26, 4
	s_lshl_b32 s10, s31, 12
	v_lshl_add_u64 v[50:51], v[8:9], 0, s[10:11]
	global_store_dwordx2 v[50:51], v[52:53], off
	s_add_i32 s31, s27, 4
	s_cmp_lt_i32 s31, s25
	s_cbranch_scc1 .LplB_skip4
	s_add_i32 s53, s29, 4
	v_readlane_b32 s43, v23, s53
	s_waitcnt vmcnt(19)
	v_lshlrev_b32_e32 v44, 16, v118
	v_and_b32_e32 v45, 0xffff0000, v118
	v_lshlrev_b32_e32 v46, 16, v119
	v_and_b32_e32 v47, 0xffff0000, v119
	s_nop 1
	v_fma_f32 v24, -v44, s43, v24
	v_fma_f32 v25, -v45, s43, v25
	v_fma_f32 v26, -v46, s43, v26
	v_fma_f32 v27, -v47, s43, v27
.LplB_skip4:
	s_add_i32 s31, s26, 12
	s_min_i32 s31, s31, 0x1fff
	s_lshl_b32 s10, s31, 12
	v_lshl_add_u64 v[48:49], v[10:11], 0, s[10:11]
	global_load_dwordx2 v[116:117], v[48:49], off
	s_add_i32 s31, s27, 12
	s_max_i32 s31, s31, s25
	s_min_i32 s31, s31, 0x1fff
	s_lshl_b32 s10, s31, 12
	v_lshl_add_u64 v[48:49], v[10:11], 0, s[10:11]
	global_load_dwordx2 v[118:119], v[48:49], off
	s_add_i32 s53, s28, 5
	v_readlane_b32 s42, v23, s53
	s_add_i32 s31, s30, 6
	s_cmp_ge_i32 s31, s17
	s_cbranch_scc1 .LplB_invw5
	v_cvt_f32_i32_e32 v29, s31
	v_div_scale_f32 v30, vcc, v29, v29, 1.0
	v_rcp_f32_e32 v31, v30
	v_div_scale_f32 v32, vcc, 1.0, v29, 1.0
	v_fma_f32 v33, -v30, v31, 1.0
	v_fmac_f32_e32 v31, v33, v31
	v_mul_f32_e32 v33, v32, v31
	v_fma_f32 v34, -v30, v33, v32
	v_fmac_f32_e32 v33, v34, v31
	v_fma_f32 v30, -v30, v33, v32
	v_div_fmas_f32 v30, v30, v31, v33
	v_div_fixup_f32 v28, v30, v29, 1.0
	s_branch .LplB_invd5

; __device__ __forceinline__ unsigned pk2(float lo, float hi) { f32x2 v = {lo, hi}; bf16x2_t b = __builtin_convertvector(v, bf16x2_t); return __builtin_bit_cast(unsigned, b); }
; __device__ __forceinline__ float bflo(unsigned w) { return __uint_as_float(w << 16); }
; __device__ __forceinline__ float bfhi(unsigned w) { return __uint_as_float(w & 0xffff0000u); }
; __device__ __forceinline__ f32x4 ldx4(const float* x, const bf16_t* x16, size_t idx) {
;     if (x16) { const u32x2 w = *(const u32x2*)(x16 + idx); return (f32x4){bflo(w.x), bfhi(w.x), bflo(w.y), bfhi(w.y)}; }
;     return *(const f32x4*)(x + idx);
; __device__ __forceinline__ void pool_phase(const float* __restrict__ x, const bf16_t* __restrict__ x16, const float* __restrict__ g, const float* rsq, bf16_t* __restrict__ pooled, LAS unsigned char* lds, int tid, int wid, int lane, int bid) {
;     ...
;         for (int tt = 0; tt < 32; ++tt) { const int r = t0 + tt;
;             const f32x4 h = ldx4(x, x16, (size_t)r * DM + c) * rs[15 + tt];
;             S += h;
;             const int tin = r - bstart; const float inv = 1.0f / (float)(tin + 1 < w ? tin + 1 : w);
;             const f32x4 p = (S * inv - h) * gv;
;             u32x2 o; o.x = pk2(p[0], p[1]); o.y = pk2(p[2], p[3]); *(u32x2*)(pooled + (size_t)r * DM + c) = o;
;             const int ro = r - w + 1; if (ro >= bstart) S -= ldx4(x, x16, (size_t)ro * DM + c) * rs[ro - (t0 - 15)]; }
.LplB_invd5:
	s_waitcnt vmcnt(20)
	v_lshlrev_b32_e32 v44, 16, v120
	v_and_b32_e32 v45, 0xffff0000, v120
	v_lshlrev_b32_e32 v46, 16, v121
	v_and_b32_e32 v47, 0xffff0000, v121
	v_mul_f32_e32 v36, s42, v44
	v_mul_f32_e32 v37, s42, v45
	v_mul_f32_e32 v38, s42, v46
	v_mul_f32_e32 v39, s42, v47
	v_fma_f32 v24, v44, s42, v24
	v_fma_f32 v25, v45, s42, v25
	v_fma_f32 v26, v46, s42, v26
	v_fma_f32 v27, v47, s42, v27
	v_fma_f32 v40, v28, v24, -v36
	v_fma_f32 v41, v28, v25, -v37
	v_fma_f32 v42, v28, v26, -v38
	v_fma_f32 v43, v28, v27, -v39
	v_mul_f32_e32 v40, v0, v40
	v_mul_f32_e32 v41, v1, v41
	v_mul_f32_e32 v42, v2, v42
	v_mul_f32_e32 v43, v3, v43
	v_cvt_pk_bf16_f32 v52, v40, v41
	v_cvt_pk_bf16_f32 v53, v42, v43
	s_add_i32 s31, s26, 5
	s_lshl_b32 s10, s31, 12
	v_lshl_add_u64 v[50:51], v[8:9], 0, s[10:11]
	global_store_dwordx2 v[50:51], v[52:53], off
	s_add_i32 s31, s27, 5
	s_cmp_lt_i32 s31, s25
	s_cbranch_scc1 .LplB_skip5
	s_add_i32 s53, s29, 5
	v_readlane_b32 s43, v23, s53
	s_waitcnt vmcnt(20)
	v_lshlrev_b32_e32 v44, 16, v122
	v_and_b32_e32 v45, 0xffff0000, v122
	v_lshlrev_b32_e32 v46, 16, v123
	v_and_b32_e32 v47, 0xffff0000, v123
	s_nop 1
	v_fma_f32 v24, -v44, s43, v24
	v_fma_f32 v25, -v45, s43, v25
	v_fma_f32 v26, -v46, s43, v26
	v_fma_f32 v27, -v47, s43, v27
.LplB_skip5:
	s_add_i32 s31, s26, 13
	s_min_i32 s31, s31, 0x1fff
	s_lshl_b32 s10, s31, 12
	v_lshl_add_u64 v[48:49], v[10:11], 0, s[10:11]
	global_load_dwordx2 v[120:121], v[48:49], off
	s_add_i32 s31, s27, 13
	s_max_i32 s31, s31, s25
	s_min_i32 s31, s31, 0x1fff
	s_lshl_b32 s10, s31, 12
	v_lshl_add_u64 v[48:49], v[10:11], 0, s[10:11]
	global_load_dwordx2 v[122:123], v[48:49], off
	s_add_i32 s53, s28, 6
	v_readlane_b32 s42, v23, s53
	s_add_i32 s31, s30, 7
	s_cmp_ge_i32 s31, s17
	s_cbranch_scc1 .LplB_invw6
	v_cvt_f32_i32_e32 v29, s31
	v_div_scale_f32 v30, vcc, v29, v29, 1.0
	v_rcp_f32_e32 v31, v30
	v_div_scale_f32 v32, vcc, 1.0, v29, 1.0
	v_fma_f32 v33, -v30, v31, 1.0
	v_fmac_f32_e32 v31, v33, v31
	v_mul_f32_e32 v33, v32, v31
	v_fma_f32 v34, -v30, v33, v32
	v_fmac_f32_e32 v33, v34, v31
	v_fma_f32 v30, -v30, v33, v32
	v_div_fmas_f32 v30, v30, v31, v33
	v_div_fixup_f32 v28, v30, v29, 1.0
	s_branch .LplB_invd6

; __device__ __forceinline__ unsigned pk2(float lo, float hi) { f32x2 v = {lo, hi}; bf16x2_t b = __builtin_convertvector(v, bf16x2_t); return __builtin_bit_cast(unsigned, b); }
; __device__ __forceinline__ float bflo(unsigned w) { return __uint_as_float(w << 16); }
; __device__ __forceinline__ float bfhi(unsigned w) { return __uint_as_float(w & 0xffff0000u); }
; __device__ __forceinline__ f32x4 ldx4(const float* x, const bf16_t* x16, size_t idx) {
;     if (x16) { const u32x2 w = *(const u32x2*)(x16 + idx); return (f32x4){bflo(w.x), bfhi(w.x), bflo(w.y), bfhi(w.y)}; }
;     return *(const f32x4*)(x + idx);
; __device__ __forceinline__ void pool_phase(const float* __restrict__ x, const bf16_t* __restrict__ x16, const float* __restrict__ g, const float* rsq, bf16_t* __restrict__ pooled, LAS unsigned char* lds, int tid, int wid, int lane, int bid) {
;     ...
;         for (int tt = 0; tt < 32; ++tt) { const int r = t0 + tt;
;             const f32x4 h = ldx4(x, x16, (size_t)r * DM + c) * rs[15 + tt];
;             S += h;
;             const int tin = r - bstart; const float inv = 1.0f / (float)(tin + 1 < w ? tin + 1 : w);
;             const f32x4 p = (S * inv - h) * gv;
;             u32x2 o; o.x = pk2(p[0], p[1]); o.y = pk2(p[2], p[3]); *(u32x2*)(pooled + (size_t)r * DM + c) = o;
;             const int ro = r - w + 1; if (ro >= bstart) S -= ldx4(x, x16, (size_t)ro * DM + c) * rs[ro - (t0 - 15)]; }
.LplB_invd6:
	s_waitcnt vmcnt(21)
	v_lshlrev_b32_e32 v44, 16, v124
	v_and_b32_e32 v45, 0xffff0000, v124
	v_lshlrev_b32_e32 v46, 16, v125
	v_and_b32_e32 v47, 0xffff0000, v125
	v_mul_f32_e32 v36, s42, v44
	v_mul_f32_e32 v37, s42, v45
	v_mul_f32_e32 v38, s42, v46
	v_mul_f32_e32 v39, s42, v47
	v_fma_f32 v24, v44, s42, v24
	v_fma_f32 v25, v45, s42, v25
	v_fma_f32 v26, v46, s42, v26
	v_fma_f32 v27, v47, s42, v27
	v_fma_f32 v40, v28, v24, -v36
	v_fma_f32 v41, v28, v25, -v37
	v_fma_f32 v42, v28, v26, -v38
	v_fma_f32 v43, v28, v27, -v39
	v_mul_f32_e32 v40, v0, v40
	v_mul_f32_e32 v41, v1, v41
	v_mul_f32_e32 v42, v2, v42
	v_mul_f32_e32 v43, v3, v43
	v_cvt_pk_bf16_f32 v52, v40, v41
	v_cvt_pk_bf16_f32 v53, v42, v43
	s_add_i32 s31, s26, 6
	s_lshl_b32 s10, s31, 12
	v_lshl_add_u64 v[50:51], v[8:9], 0, s[10:11]
	global_store_dwordx2 v[50:51], v[52:53], off
	s_add_i32 s31, s27, 6
	s_cmp_lt_i32 s31, s25
	s_cbranch_scc1 .LplB_skip6
	s_add_i32 s53, s29, 6
	v_readlane_b32 s43, v23, s53
	s_waitcnt vmcnt(21)
	v_lshlrev_b32_e32 v44, 16, v126
	v_and_b32_e32 v45, 0xffff0000, v126
	v_lshlrev_b32_e32 v46, 16, v127
	v_and_b32_e32 v47, 0xffff0000, v127
	s_nop 1
	v_fma_f32 v24, -v44, s43, v24
	v_fma_f32 v25, -v45, s43, v25
	v_fma_f32 v26, -v46, s43, v26
	v_fma_f32 v27, -v47, s43, v27
.LplB_skip6:
	s_add_i32 s31, s26, 14
	s_min_i32 s31, s31, 0x1fff
	s_lshl_b32 s10, s31, 12
	v_lshl_add_u64 v[48:49], v[10:11], 0, s[10:11]
	global_load_dwordx2 v[124:125], v[48:49], off
	s_add_i32 s31, s27, 14
	s_max_i32 s31, s31, s25
	s_min_i32 s31, s31, 0x1fff
	s_lshl_b32 s10, s31, 12
	v_lshl_add_u64 v[48:49], v[10:11], 0, s[10:11]
	global_load_dwordx2 v[126:127], v[48:49], off
	s_add_i32 s53, s28, 7
	v_readlane_b32 s42, v23, s53
	s_add_i32 s31, s30, 8
	s_cmp_ge_i32 s31, s17
	s_cbranch_scc1 .LplB_invw7
	v_cvt_f32_i32_e32 v29, s31
	v_div_scale_f32 v30, vcc, v29, v29, 1.0
	v_rcp_f32_e32 v31, v30
	v_div_scale_f32 v32, vcc, 1.0, v29, 1.0
	v_fma_f32 v33, -v30, v31, 1.0
	v_fmac_f32_e32 v31, v33, v31
	v_mul_f32_e32 v33, v32, v31
	v_fma_f32 v34, -v30, v33, v32
	v_fmac_f32_e32 v33, v34, v31
	v_fma_f32 v30, -v30, v33, v32
	v_div_fmas_f32 v30, v30, v31, v33
	v_div_fixup_f32 v28, v30, v29, 1.0
	s_branch .LplB_invd7

; __device__ __forceinline__ unsigned pk2(float lo, float hi) { f32x2 v = {lo, hi}; bf16x2_t b = __builtin_convertvector(v, bf16x2_t); return __builtin_bit_cast(unsigned, b); }
; __device__ __forceinline__ float bflo(unsigned w) { return __uint_as_float(w << 16); }
; __device__ __forceinline__ float bfhi(unsigned w) { return __uint_as_float(w & 0xffff0000u); }
; __device__ __forceinline__ f32x4 ldx4(const float* x, const bf16_t* x16, size_t idx) {
;     if (x16) { const u32x2 w = *(const u32x2*)(x16 + idx); return (f32x4){bflo(w.x), bfhi(w.x), bflo(w.y), bfhi(w.y)}; }
;     return *(const f32x4*)(x + idx);
; __device__ __forceinline__ void pool_phase(const float* __restrict__ x, const bf16_t* __restrict__ x16, const float* __restrict__ g, const float* rsq, bf16_t* __restrict__ pooled, LAS unsigned char* lds, int tid, int wid, int lane, int bid) {
;     ...
;         for (int tt = 0; tt < 32; ++tt) { const int r = t0 + tt;
;             const f32x4 h = ldx4(x, x16, (size_t)r * DM + c) * rs[15 + tt];
;             S += h;
;             const int tin = r - bstart; const float inv = 1.0f / (float)(tin + 1 < w ? tin + 1 : w);
;             const f32x4 p = (S * inv - h) * gv;
;             u32x2 o; o.x = pk2(p[0], p[1]); o.y = pk2(p[2], p[3]); *(u32x2*)(pooled + (size_t)r * DM + c) = o;
;             const int ro = r - w + 1; if (ro >= bstart) S -= ldx4(x, x16, (size_t)ro * DM + c) * rs[ro - (t0 - 15)]; }
.LplB_invd7:
	s_waitcnt vmcnt(22)
	v_lshlrev_b32_e32 v44, 16, v128
	v_and_b32_e32 v45, 0xffff0000, v128
	v_lshlrev_b32_e32 v46, 16, v129
	v_and_b32_e32 v47, 0xffff0000, v129
	v_mul_f32_e32 v36, s42, v44
	v_mul_f32_e32 v37, s42, v45
	v_mul_f32_e32 v38, s42, v46
	v_mul_f32_e32 v39, s42, v47
	v_fma_f32 v24, v44, s42, v24
	v_fma_f32 v25, v45, s42, v25
	v_fma_f32 v26, v46, s42, v26
	v_fma_f32 v27, v47, s42, v27
	v_fma_f32 v40, v28, v24, -v36
	v_fma_f32 v41, v28, v25, -v37
	v_fma_f32 v42, v28, v26, -v38
	v_fma_f32 v43, v28, v27, -v39
	v_mul_f32_e32 v40, v0, v40
	v_mul_f32_e32 v41, v1, v41
	v_mul_f32_e32 v42, v2, v42
	v_mul_f32_e32 v43, v3, v43
	v_cvt_pk_bf16_f32 v52, v40, v41
	v_cvt_pk_bf16_f32 v53, v42, v43
	s_add_i32 s31, s26, 7
	s_lshl_b32 s10, s31, 12
	v_lshl_add_u64 v[50:51], v[8:9], 0, s[10:11]
	global_store_dwordx2 v[50:51], v[52:53], off
	s_add_i32 s31, s27, 7
	s_cmp_lt_i32 s31, s25
	s_cbranch_scc1 .LplB_skip7
	s_add_i32 s53, s29, 7
	v_readlane_b32 s43, v23, s53
	s_waitcnt vmcnt(22)
	v_lshlrev_b32_e32 v44, 16, v130
	v_and_b32_e32 v45, 0xffff0000, v130
	v_lshlrev_b32_e32 v46, 16, v131
	v_and_b32_e32 v47, 0xffff0000, v131
	s_nop 1
	v_fma_f32 v24, -v44, s43, v24
	v_fma_f32 v25, -v45, s43, v25
	v_fma_f32 v26, -v46, s43, v26
	v_fma_f32 v27, -v47, s43, v27
